# MLA: second max chain interleaved with the PV MFMAs so only the rescale test is left behind the barrier
# speedup vs baseline: 1.0142x; 1.0131x over previous
; __device__ __forceinline__ void finishSM9(f32x16& p0, f32x16& p1, float alpha, float& l_reg, v8i32& p8) {
; #pragma unroll
;   for (int r = 0; r < 16; ++r) { p0[r] = __builtin_amdgcn_exp2f(p0[r]); p1[r] = __builtin_amdgcn_exp2f(p1[r]); }
;   float ps = 0;
; #pragma unroll
;   for (int r = 0; r < 16; ++r) ps += p0[r];
; #pragma unroll
;   for (int r = 0; r < 16; ++r) ps += p1[r];
;   { auto rr = __builtin_amdgcn_permlane32_swap(__float_as_uint(ps), __float_as_uint(ps), false, false);
;     ps = __uint_as_float(rr[0]) + __uint_as_float(rr[1]); }
;   l_reg = l_reg * alpha + ps;
; #pragma unroll
;   for (int g = 0; g < 4; ++g) {
;     int w = __builtin_amdgcn_cvt_pk_fp8_f32(p0[4 * g], p0[4 * g + 1], 0, false); p8[g] = __builtin_amdgcn_cvt_pk_fp8_f32(p0[4 * g + 2], p0[4 * g + 3], w, true);
;     int u = __builtin_amdgcn_cvt_pk_fp8_f32(p1[4 * g], p1[4 * g + 1], 0, false); p8[4 + g] = __builtin_amdgcn_cvt_pk_fp8_f32(p1[4 * g + 2], p1[4 * g + 3], u, true); }
; }
; __device__ __forceinline__ void pv8(f32x16* o, const char* Vt, const v8i32 p8, int r32, int hi) {
;   const int sw = (r32 >> 2) & 3, a0 = r32 * 64 + (((hi * 2) ^ sw) << 4), a1 = r32 * 64 + (((hi * 2 + 1) ^ sw) << 4);
; #pragma unroll
;   for (int d0 = 0; d0 < 4; ++d0) {
;     const v8i32 vf = cat8(*reinterpret_cast<const v4i32*>(Vt + d0 * 2048 + a0), *reinterpret_cast<const v4i32*>(Vt + d0 * 2048 + a1));
;     o[d0] = __builtin_amdgcn_mfma_scale_f32_32x32x64_f8f6f4(p8, vf, o[d0], 0, 0, 0, 127, 0, 127); }
; }
; __device__ __forceinline__ void qkt9(f32x16& p0, f32x16& p1, const char* Kn, const char* Kr, const v8i32* qf, const float init, int r32, int hi) {
; #pragma unroll
;   for (int r = 0; r < 16; ++r) { p0[r] = init; p1[r] = init; }
; #pragma unroll
;   for (int s = 0; s < 2; ++s) { const int c0 = s * 4 + hi * 2;
;     const v8i32 a0 = cat8(*reinterpret_cast<const v4i32*>(Kn + KN8SW(r32, c0)), *reinterpret_cast<const v4i32*>(Kn + KN8SW(r32, c0 + 1)));
;     const v8i32 a1 = cat8(*reinterpret_cast<const v4i32*>(Kn + 4096 + KN8SW(r32, c0)), *reinterpret_cast<const v4i32*>(Kn + 4096 + KN8SW(r32, c0 + 1)));
;     p0 = __builtin_amdgcn_mfma_scale_f32_32x32x64_f8f6f4(a0, qf[s], p0, 0, 0, 0, 127, 0, 124);
;     p1 = __builtin_amdgcn_mfma_scale_f32_32x32x64_f8f6f4(a1, qf[s], p1, 0, 0, 0, 127, 0, 124); }
;   { const int c0 = hi * 2;
.LBB0_1321:
	global_load_dwordx4 v[158:161], v176, s[18:19]
	global_load_dwordx4 v[162:165], v178, s[16:17]
	global_load_dwordx4 v[154:157], v[180:181], off
	ds_read_b128 v[114:117], v215 offset:24576
	ds_read_b128 v[118:121], v216 offset:24576
	ds_read_b128 v[222:225], v215 offset:28672
	ds_read_b128 v[226:229], v216 offset:28672
	v_exp_f32_e32 v0, v82
	v_exp_f32_e32 v177, v83
	v_exp_f32_e32 v179, v84
	v_exp_f32_e32 v254, v85
	v_add_f32_e32 v219, v0, v177
	v_cvt_pk_fp8_f32 v246, v0, v177
	v_add_f32_e32 v219, v179, v219
	v_add_f32_e32 v219, v254, v219
	v_cvt_pk_fp8_f32 v246, v179, v254 op_sel:[0,0,1]
	s_waitcnt lgkmcnt(2)
	v_mfma_scale_f32_32x32x64_f8f6f4 v[114:129], v[114:121], v[146:153], v[230:245], v194, v193 op_sel_hi:[0,0,0]
	v_exp_f32_e32 v0, v86
	v_exp_f32_e32 v177, v87
	v_exp_f32_e32 v179, v88
	v_exp_f32_e32 v254, v89
	v_add_f32_e32 v219, v0, v219
	v_add_f32_e32 v219, v177, v219
	v_cvt_pk_fp8_f32 v247, v0, v177
	v_add_f32_e32 v219, v179, v219
	v_add_f32_e32 v219, v254, v219
	v_cvt_pk_fp8_f32 v247, v179, v254 op_sel:[0,0,1]
	ds_read_b128 v[82:85], v213 offset:24576
	ds_read_b128 v[86:89], v214 offset:24576
	s_waitcnt lgkmcnt(2)
	v_mfma_scale_f32_32x32x64_f8f6f4 v[98:113], v[222:229], v[146:153], v[230:245], v194, v193 op_sel_hi:[0,0,0]
	ds_read_b128 v[222:225], v213 offset:28672
	ds_read_b128 v[226:229], v214 offset:28672
	v_exp_f32_e32 v0, v90
	v_exp_f32_e32 v177, v91
	v_exp_f32_e32 v179, v92
	v_exp_f32_e32 v254, v93
	v_add_f32_e32 v219, v0, v219
	v_add_f32_e32 v219, v177, v219
	v_cvt_pk_fp8_f32 v248, v0, v177
	v_add_f32_e32 v219, v179, v219
	v_add_f32_e32 v219, v254, v219
	v_cvt_pk_fp8_f32 v248, v179, v254 op_sel:[0,0,1]
	v_exp_f32_e32 v0, v94
	v_exp_f32_e32 v177, v95
	v_exp_f32_e32 v179, v96
	v_exp_f32_e32 v254, v97
	v_add_f32_e32 v219, v0, v219
	v_add_f32_e32 v219, v177, v219
	v_cvt_pk_fp8_f32 v249, v0, v177
	v_add_f32_e32 v219, v179, v219
	v_add_f32_e32 v219, v254, v219
	v_cvt_pk_fp8_f32 v249, v179, v254 op_sel:[0,0,1]
	ds_read_b128 v[90:93], v185 offset:36864
	ds_read_b128 v[94:97], v186 offset:36864
	s_waitcnt lgkmcnt(4)
	v_mfma_scale_f32_32x32x64_f8f6f4 v[114:129], v[82:89], v[138:145], v[114:129], v194, v193 op_sel_hi:[0,0,0]
	v_exp_f32_e32 v0, v66
	v_exp_f32_e32 v177, v67
	v_exp_f32_e32 v179, v68
	v_exp_f32_e32 v254, v69
	v_add_f32_e32 v219, v0, v219
	v_add_f32_e32 v219, v177, v219
	v_cvt_pk_fp8_f32 v250, v0, v177
	v_add_f32_e32 v219, v179, v219
	v_add_f32_e32 v219, v254, v219
	v_cvt_pk_fp8_f32 v250, v179, v254 op_sel:[0,0,1]
	s_waitcnt lgkmcnt(2)
	v_mfma_scale_f32_32x32x64_f8f6f4 v[98:113], v[222:229], v[138:145], v[98:113], v194, v193 op_sel_hi:[0,0,0]
	ds_read_b128 v[222:225], v185 offset:38912
	ds_read_b128 v[226:229], v186 offset:38912
	v_exp_f32_e32 v0, v70
	v_exp_f32_e32 v177, v71
	v_exp_f32_e32 v179, v72
	v_exp_f32_e32 v254, v73
	v_add_f32_e32 v219, v0, v219
	v_add_f32_e32 v219, v177, v219
	v_cvt_pk_fp8_f32 v251, v0, v177
	v_add_f32_e32 v219, v179, v219
	v_add_f32_e32 v219, v254, v219
	v_cvt_pk_fp8_f32 v251, v179, v254 op_sel:[0,0,1]
	v_exp_f32_e32 v0, v74
	v_exp_f32_e32 v177, v75
	v_exp_f32_e32 v179, v76
	v_exp_f32_e32 v254, v77
	v_add_f32_e32 v219, v0, v219
	v_add_f32_e32 v219, v177, v219
	v_cvt_pk_fp8_f32 v252, v0, v177
	v_add_f32_e32 v219, v179, v219
	v_add_f32_e32 v219, v254, v219
	v_cvt_pk_fp8_f32 v252, v179, v254 op_sel:[0,0,1]
	s_waitcnt lgkmcnt(2)
	v_mfma_scale_f32_32x32x64_f8f6f4 v[114:129], v[90:97], v[130:137], v[114:129], v194, v193 op_sel_hi:[0,0,0]
	v_exp_f32_e32 v0, v78
	v_exp_f32_e32 v177, v79
	v_exp_f32_e32 v179, v80
	v_exp_f32_e32 v254, v81
	v_add_f32_e32 v219, v0, v219
	v_add_f32_e32 v219, v177, v219
	v_cvt_pk_fp8_f32 v253, v0, v177
	v_add_f32_e32 v219, v179, v219
	v_add_f32_e32 v219, v254, v219
	v_cvt_pk_fp8_f32 v253, v179, v254 op_sel:[0,0,1]
	ds_read_b128 v[90:93], v185 offset:0
	ds_read_b128 v[94:97], v186 offset:0
	ds_read_b128 v[82:85], v185 offset:2048
	ds_read_b128 v[86:89], v186 offset:2048
	ds_read_b128 v[74:77], v185 offset:4096
	ds_read_b128 v[78:81], v186 offset:4096
	ds_read_b128 v[66:69], v185 offset:6144
	ds_read_b128 v[70:73], v186 offset:6144
	s_waitcnt lgkmcnt(8)
	v_mfma_scale_f32_32x32x64_f8f6f4 v[98:113], v[222:229], v[130:137], v[98:113], v194, v193 op_sel_hi:[0,0,0]
	v_mov_b32_e32 v0, v219
	s_nop 1
	v_permlane32_swap_b32_e32 v219, v0
	v_add_f32_e32 v219, v219, v0
	v_fma_f32 v209, v209, v218, v219
	v_add_u32_e32 v176, 0x2000, v176
	v_add_u32_e32 v178, 0x20000, v178
	s_mov_b64 s[20:21], 0x1000
	v_lshl_add_u64 v[180:181], v[180:181], 0, s[20:21]
	v_max_f32_e32 v177, v114, v115
	v_max3_f32 v177, v177, v116, v117
	v_max3_f32 v177, v177, v118, v119
	v_max3_f32 v177, v177, v120, v121
	v_max3_f32 v177, v177, v122, v123
	v_max3_f32 v177, v177, v124, v125
	v_max3_f32 v177, v177, v126, v127
	v_max3_f32 v177, v177, v128, v129
	s_waitcnt lgkmcnt(6)
	v_mfma_scale_f32_32x32x64_f8f6f4 v[50:65], v[246:253], v[90:97], v[50:65], v194, v194 op_sel_hi:[0,0,0]
	v_max_f32_e32 v0, v98, v99
	v_max3_f32 v0, v0, v100, v101
	v_max3_f32 v0, v0, v102, v103
	s_waitcnt lgkmcnt(4)
	v_mfma_scale_f32_32x32x64_f8f6f4 v[34:49], v[246:253], v[82:89], v[34:49], v194, v194 op_sel_hi:[0,0,0]
	v_max3_f32 v0, v0, v104, v105
	v_max3_f32 v0, v0, v106, v107
	v_max3_f32 v0, v0, v108, v109
	s_waitcnt lgkmcnt(2)
	v_mfma_scale_f32_32x32x64_f8f6f4 v[18:33], v[246:253], v[74:81], v[18:33], v194, v194 op_sel_hi:[0,0,0]
	v_max3_f32 v0, v0, v110, v111
	v_max3_f32 v0, v0, v112, v113
	v_max_f32_e32 v177, v177, v0
	v_mov_b32_e32 v0, v177
	v_mov_b32_e32 v221, 1.0
	s_waitcnt vmcnt(0)
	ds_write_b128 v210, v[158:161] offset:43008
	ds_write_b128 v211, v[162:165] offset:51200
	ds_write_b128 v212, v[154:157] offset:59392
	s_waitcnt lgkmcnt(3)
	v_mfma_scale_f32_32x32x64_f8f6f4 v[2:17], v[246:253], v[66:73], v[2:17], v194, v194 op_sel_hi:[0,0,0]
	s_waitcnt lgkmcnt(0)
	s_barrier
	v_permlane32_swap_b32_e32 v177, v0
	v_max_f32_e32 v177, v177, v0
	v_cmp_ge_f32_e32 vcc, s90, v177
	s_cmp_eq_u64 vcc, exec
	s_cbranch_scc0 .Lmla_h0_newmax
; __device__ __forceinline__ void finishSM9(f32x16& p0, f32x16& p1, float alpha, float& l_reg, v8i32& p8) {
; #pragma unroll
;   for (int r = 0; r < 16; ++r) { p0[r] = __builtin_amdgcn_exp2f(p0[r]); p1[r] = __builtin_amdgcn_exp2f(p1[r]); }
;   float ps = 0;
; #pragma unroll
;   for (int r = 0; r < 16; ++r) ps += p0[r];
; #pragma unroll
;   for (int r = 0; r < 16; ++r) ps += p1[r];
;   { auto rr = __builtin_amdgcn_permlane32_swap(__float_as_uint(ps), __float_as_uint(ps), false, false);
;     ps = __uint_as_float(rr[0]) + __uint_as_float(rr[1]); }
;   l_reg = l_reg * alpha + ps;
; #pragma unroll
;   for (int g = 0; g < 4; ++g) {
;     int w = __builtin_amdgcn_cvt_pk_fp8_f32(p0[4 * g], p0[4 * g + 1], 0, false); p8[g] = __builtin_amdgcn_cvt_pk_fp8_f32(p0[4 * g + 2], p0[4 * g + 3], w, true);
;     int u = __builtin_amdgcn_cvt_pk_fp8_f32(p1[4 * g], p1[4 * g + 1], 0, false); p8[4 + g] = __builtin_amdgcn_cvt_pk_fp8_f32(p1[4 * g + 2], p1[4 * g + 3], u, true); }
; }
; __device__ __forceinline__ void pv8(f32x16* o, const char* Vt, const v8i32 p8, int r32, int hi) {
;   const int sw = (r32 >> 2) & 3, a0 = r32 * 64 + (((hi * 2) ^ sw) << 4), a1 = r32 * 64 + (((hi * 2 + 1) ^ sw) << 4);
; #pragma unroll
;   for (int d0 = 0; d0 < 4; ++d0) {
;     const v8i32 vf = cat8(*reinterpret_cast<const v4i32*>(Vt + d0 * 2048 + a0), *reinterpret_cast<const v4i32*>(Vt + d0 * 2048 + a1));
;     o[d0] = __builtin_amdgcn_mfma_scale_f32_32x32x64_f8f6f4(p8, vf, o[d0], 0, 0, 0, 127, 0, 127); }
; }
; __device__ __forceinline__ void qkt9(f32x16& p0, f32x16& p1, const char* Kn, const char* Kr, const v8i32* qf, const float init, int r32, int hi) {
; #pragma unroll
;   for (int r = 0; r < 16; ++r) { p0[r] = init; p1[r] = init; }
; #pragma unroll
;   for (int s = 0; s < 2; ++s) { const int c0 = s * 4 + hi * 2;
;     const v8i32 a0 = cat8(*reinterpret_cast<const v4i32*>(Kn + KN8SW(r32, c0)), *reinterpret_cast<const v4i32*>(Kn + KN8SW(r32, c0 + 1)));
;     const v8i32 a1 = cat8(*reinterpret_cast<const v4i32*>(Kn + 4096 + KN8SW(r32, c0)), *reinterpret_cast<const v4i32*>(Kn + 4096 + KN8SW(r32, c0 + 1)));
;     p0 = __builtin_amdgcn_mfma_scale_f32_32x32x64_f8f6f4(a0, qf[s], p0, 0, 0, 0, 127, 0, 124);
;     p1 = __builtin_amdgcn_mfma_scale_f32_32x32x64_f8f6f4(a1, qf[s], p1, 0, 0, 0, 127, 0, 124); }
;   { const int c0 = hi * 2;
.Lmla_h0_cont:
	global_load_dwordx4 v[158:161], v176, s[18:19]
	global_load_dwordx4 v[162:165], v178, s[16:17]
	global_load_dwordx4 v[154:157], v[180:181], off
	ds_read_b128 v[82:85], v215 offset:51200
	ds_read_b128 v[86:89], v216 offset:51200
	ds_read_b128 v[222:225], v215 offset:55296
	ds_read_b128 v[226:229], v216 offset:55296
	v_exp_f32_e32 v0, v114
	v_exp_f32_e32 v177, v115
	v_exp_f32_e32 v179, v116
	v_exp_f32_e32 v254, v117
	v_add_f32_e32 v219, v0, v177
	v_cvt_pk_fp8_f32 v246, v0, v177
	v_add_f32_e32 v219, v179, v219
	v_add_f32_e32 v219, v254, v219
	v_cvt_pk_fp8_f32 v246, v179, v254 op_sel:[0,0,1]
	s_waitcnt lgkmcnt(2)
	v_mfma_scale_f32_32x32x64_f8f6f4 v[82:97], v[82:89], v[146:153], v[230:245], v194, v193 op_sel_hi:[0,0,0]
	v_exp_f32_e32 v0, v118
	v_exp_f32_e32 v177, v119
	v_exp_f32_e32 v179, v120
	v_exp_f32_e32 v254, v121
	v_add_f32_e32 v219, v0, v219
	v_add_f32_e32 v219, v177, v219
	v_cvt_pk_fp8_f32 v247, v0, v177
	v_add_f32_e32 v219, v179, v219
	v_add_f32_e32 v219, v254, v219
	v_cvt_pk_fp8_f32 v247, v179, v254 op_sel:[0,0,1]
	ds_read_b128 v[114:117], v213 offset:51200
	ds_read_b128 v[118:121], v214 offset:51200
	s_waitcnt lgkmcnt(2)
	v_mfma_scale_f32_32x32x64_f8f6f4 v[66:81], v[222:229], v[146:153], v[230:245], v194, v193 op_sel_hi:[0,0,0]
	ds_read_b128 v[222:225], v213 offset:55296
	ds_read_b128 v[226:229], v214 offset:55296
	v_exp_f32_e32 v0, v122
	v_exp_f32_e32 v177, v123
	v_exp_f32_e32 v179, v124
	v_exp_f32_e32 v254, v125
	v_add_f32_e32 v219, v0, v219
	v_add_f32_e32 v219, v177, v219
	v_cvt_pk_fp8_f32 v248, v0, v177
	v_add_f32_e32 v219, v179, v219
	v_add_f32_e32 v219, v254, v219
	v_cvt_pk_fp8_f32 v248, v179, v254 op_sel:[0,0,1]
	v_exp_f32_e32 v0, v126
	v_exp_f32_e32 v177, v127
	v_exp_f32_e32 v179, v128
	v_exp_f32_e32 v254, v129
	v_add_f32_e32 v219, v0, v219
	v_add_f32_e32 v219, v177, v219
	v_cvt_pk_fp8_f32 v249, v0, v177
	v_add_f32_e32 v219, v179, v219
	v_add_f32_e32 v219, v254, v219
	v_cvt_pk_fp8_f32 v249, v179, v254 op_sel:[0,0,1]
	ds_read_b128 v[122:125], v185 offset:59392
	ds_read_b128 v[126:129], v186 offset:59392
	s_waitcnt lgkmcnt(4)
	v_mfma_scale_f32_32x32x64_f8f6f4 v[82:97], v[114:121], v[138:145], v[82:97], v194, v193 op_sel_hi:[0,0,0]
	v_exp_f32_e32 v0, v98
	v_exp_f32_e32 v177, v99
	v_exp_f32_e32 v179, v100
	v_exp_f32_e32 v254, v101
	v_add_f32_e32 v219, v0, v219
	v_add_f32_e32 v219, v177, v219
	v_cvt_pk_fp8_f32 v250, v0, v177
	v_add_f32_e32 v219, v179, v219
	v_add_f32_e32 v219, v254, v219
	v_cvt_pk_fp8_f32 v250, v179, v254 op_sel:[0,0,1]
	s_waitcnt lgkmcnt(2)
	v_mfma_scale_f32_32x32x64_f8f6f4 v[66:81], v[222:229], v[138:145], v[66:81], v194, v193 op_sel_hi:[0,0,0]
	ds_read_b128 v[222:225], v185 offset:61440
	ds_read_b128 v[226:229], v186 offset:61440
	v_exp_f32_e32 v0, v102
	v_exp_f32_e32 v177, v103
	v_exp_f32_e32 v179, v104
	v_exp_f32_e32 v254, v105
	v_add_f32_e32 v219, v0, v219
	v_add_f32_e32 v219, v177, v219
	v_cvt_pk_fp8_f32 v251, v0, v177
	v_add_f32_e32 v219, v179, v219
	v_add_f32_e32 v219, v254, v219
	v_cvt_pk_fp8_f32 v251, v179, v254 op_sel:[0,0,1]
	v_exp_f32_e32 v0, v106
	v_exp_f32_e32 v177, v107
	v_exp_f32_e32 v179, v108
	v_exp_f32_e32 v254, v109
	v_add_f32_e32 v219, v0, v219
	v_add_f32_e32 v219, v177, v219
	v_cvt_pk_fp8_f32 v252, v0, v177
	v_add_f32_e32 v219, v179, v219
	v_add_f32_e32 v219, v254, v219
	v_cvt_pk_fp8_f32 v252, v179, v254 op_sel:[0,0,1]
	s_waitcnt lgkmcnt(2)
	v_mfma_scale_f32_32x32x64_f8f6f4 v[82:97], v[122:129], v[130:137], v[82:97], v194, v193 op_sel_hi:[0,0,0]
	v_exp_f32_e32 v0, v110
	v_exp_f32_e32 v177, v111
	v_exp_f32_e32 v179, v112
	v_exp_f32_e32 v254, v113
	v_add_f32_e32 v219, v0, v219
	v_add_f32_e32 v219, v177, v219
	v_cvt_pk_fp8_f32 v253, v0, v177
	v_add_f32_e32 v219, v179, v219
	v_add_f32_e32 v219, v254, v219
	v_cvt_pk_fp8_f32 v253, v179, v254 op_sel:[0,0,1]
	ds_read_b128 v[122:125], v185 offset:8192
	ds_read_b128 v[126:129], v186 offset:8192
	ds_read_b128 v[114:117], v185 offset:10240
	ds_read_b128 v[118:121], v186 offset:10240
	ds_read_b128 v[106:109], v185 offset:12288
	ds_read_b128 v[110:113], v186 offset:12288
	ds_read_b128 v[98:101], v185 offset:14336
	ds_read_b128 v[102:105], v186 offset:14336
	s_waitcnt lgkmcnt(8)
	v_mfma_scale_f32_32x32x64_f8f6f4 v[66:81], v[222:229], v[130:137], v[66:81], v194, v193 op_sel_hi:[0,0,0]
	v_mov_b32_e32 v0, v219
	s_nop 1
	v_permlane32_swap_b32_e32 v219, v0
	v_add_f32_e32 v219, v219, v0
	v_fma_f32 v209, v209, v221, v219
	v_add_u32_e32 v176, 0x2000, v176
	v_add_u32_e32 v178, 0x20000, v178
	s_mov_b64 s[20:21], 0x1000
	v_lshl_add_u64 v[180:181], v[180:181], 0, s[20:21]
	v_max_f32_e32 v177, v82, v83
	v_max3_f32 v177, v177, v84, v85
	v_max3_f32 v177, v177, v86, v87
	v_max3_f32 v177, v177, v88, v89
	v_max3_f32 v177, v177, v90, v91
	v_max3_f32 v177, v177, v92, v93
	v_max3_f32 v177, v177, v94, v95
	v_max3_f32 v177, v177, v96, v97
	s_waitcnt lgkmcnt(6)
	v_mfma_scale_f32_32x32x64_f8f6f4 v[50:65], v[246:253], v[122:129], v[50:65], v194, v194 op_sel_hi:[0,0,0]
	v_max_f32_e32 v0, v66, v67
	v_max3_f32 v0, v0, v68, v69
	v_max3_f32 v0, v0, v70, v71
	s_waitcnt lgkmcnt(4)
	v_mfma_scale_f32_32x32x64_f8f6f4 v[34:49], v[246:253], v[114:121], v[34:49], v194, v194 op_sel_hi:[0,0,0]
	v_max3_f32 v0, v0, v72, v73
	v_max3_f32 v0, v0, v74, v75
	v_max3_f32 v0, v0, v76, v77
	s_waitcnt lgkmcnt(2)
	v_mfma_scale_f32_32x32x64_f8f6f4 v[18:33], v[246:253], v[106:113], v[18:33], v194, v194 op_sel_hi:[0,0,0]
	v_max3_f32 v0, v0, v78, v79
	v_max3_f32 v0, v0, v80, v81
	v_max_f32_e32 v177, v177, v0
	v_mov_b32_e32 v0, v177
	v_mov_b32_e32 v218, 1.0
	s_waitcnt vmcnt(0)
	ds_write_b128 v210, v[158:161]
	ds_write_b128 v211, v[162:165] offset:16384
	ds_write_b128 v212, v[154:157] offset:32768
	s_waitcnt lgkmcnt(3)
	v_mfma_scale_f32_32x32x64_f8f6f4 v[2:17], v[246:253], v[98:105], v[2:17], v194, v194 op_sel_hi:[0,0,0]
	s_waitcnt lgkmcnt(0)
	s_barrier
	v_permlane32_swap_b32_e32 v177, v0
	v_max_f32_e32 v177, v177, v0
	v_cmp_ge_f32_e32 vcc, s90, v177
	s_cmp_eq_u64 vcc, exec
	s_cbranch_scc0 .Lmla_h1_newmax
; __device__ __forceinline__ void finishSM9(f32x16& p0, f32x16& p1, float alpha, float& l_reg, v8i32& p8) {
; #pragma unroll
;   for (int r = 0; r < 16; ++r) { p0[r] = __builtin_amdgcn_exp2f(p0[r]); p1[r] = __builtin_amdgcn_exp2f(p1[r]); }
;   float ps = 0;
; #pragma unroll
;   for (int r = 0; r < 16; ++r) ps += p0[r];
; #pragma unroll
;   for (int r = 0; r < 16; ++r) ps += p1[r];
;   { auto rr = __builtin_amdgcn_permlane32_swap(__float_as_uint(ps), __float_as_uint(ps), false, false);
;     ps = __uint_as_float(rr[0]) + __uint_as_float(rr[1]); }
;   l_reg = l_reg * alpha + ps;
; #pragma unroll
;   for (int g = 0; g < 4; ++g) {
;     int w = __builtin_amdgcn_cvt_pk_fp8_f32(p0[4 * g], p0[4 * g + 1], 0, false); p8[g] = __builtin_amdgcn_cvt_pk_fp8_f32(p0[4 * g + 2], p0[4 * g + 3], w, true);
;     int u = __builtin_amdgcn_cvt_pk_fp8_f32(p1[4 * g], p1[4 * g + 1], 0, false); p8[4 + g] = __builtin_amdgcn_cvt_pk_fp8_f32(p1[4 * g + 2], p1[4 * g + 3], u, true); }
; }
; __device__ __forceinline__ void pv8(f32x16* o, const char* Vt, const v8i32 p8, int r32, int hi) {
;   const int sw = (r32 >> 2) & 3, a0 = r32 * 64 + (((hi * 2) ^ sw) << 4), a1 = r32 * 64 + (((hi * 2 + 1) ^ sw) << 4);
; #pragma unroll
;   for (int d0 = 0; d0 < 4; ++d0) {
;     const v8i32 vf = cat8(*reinterpret_cast<const v4i32*>(Vt + d0 * 2048 + a0), *reinterpret_cast<const v4i32*>(Vt + d0 * 2048 + a1));
;     o[d0] = __builtin_amdgcn_mfma_scale_f32_32x32x64_f8f6f4(p8, vf, o[d0], 0, 0, 0, 127, 0, 127); }
; }
; __device__ __forceinline__ void qkt9(f32x16& p0, f32x16& p1, const char* Kn, const char* Kr, const v8i32* qf, const float init, int r32, int hi) {
; #pragma unroll
;   for (int r = 0; r < 16; ++r) { p0[r] = init; p1[r] = init; }
; #pragma unroll
;   for (int s = 0; s < 2; ++s) { const int c0 = s * 4 + hi * 2;
;     const v8i32 a0 = cat8(*reinterpret_cast<const v4i32*>(Kn + KN8SW(r32, c0)), *reinterpret_cast<const v4i32*>(Kn + KN8SW(r32, c0 + 1)));
;     const v8i32 a1 = cat8(*reinterpret_cast<const v4i32*>(Kn + 4096 + KN8SW(r32, c0)), *reinterpret_cast<const v4i32*>(Kn + 4096 + KN8SW(r32, c0 + 1)));
;     p0 = __builtin_amdgcn_mfma_scale_f32_32x32x64_f8f6f4(a0, qf[s], p0, 0, 0, 0, 127, 0, 124);
;     p1 = __builtin_amdgcn_mfma_scale_f32_32x32x64_f8f6f4(a1, qf[s], p1, 0, 0, 0, 127, 0, 124); }
;   { const int c0 = hi * 2;
.Lmla_h1_cont:
	global_load_dwordx4 v[158:161], v176, s[18:19]
	global_load_dwordx4 v[162:165], v178, s[16:17]
	global_load_dwordx4 v[154:157], v[180:181], off
	ds_read_b128 v[114:117], v215 offset:16384
	ds_read_b128 v[118:121], v216 offset:16384
	ds_read_b128 v[222:225], v215 offset:20480
	ds_read_b128 v[226:229], v216 offset:20480
	v_exp_f32_e32 v0, v82
	v_exp_f32_e32 v177, v83
	v_exp_f32_e32 v179, v84
	v_exp_f32_e32 v254, v85
	v_add_f32_e32 v219, v0, v177
	v_cvt_pk_fp8_f32 v246, v0, v177
	v_add_f32_e32 v219, v179, v219
	v_add_f32_e32 v219, v254, v219
	v_cvt_pk_fp8_f32 v246, v179, v254 op_sel:[0,0,1]
	s_waitcnt lgkmcnt(2)
	v_mfma_scale_f32_32x32x64_f8f6f4 v[114:129], v[114:121], v[146:153], v[230:245], v194, v193 op_sel_hi:[0,0,0]
	v_exp_f32_e32 v0, v86
	v_exp_f32_e32 v177, v87
	v_exp_f32_e32 v179, v88
	v_exp_f32_e32 v254, v89
	v_add_f32_e32 v219, v0, v219
	v_add_f32_e32 v219, v177, v219
	v_cvt_pk_fp8_f32 v247, v0, v177
	v_add_f32_e32 v219, v179, v219
	v_add_f32_e32 v219, v254, v219
	v_cvt_pk_fp8_f32 v247, v179, v254 op_sel:[0,0,1]
	ds_read_b128 v[82:85], v213 offset:16384
	ds_read_b128 v[86:89], v214 offset:16384
	s_waitcnt lgkmcnt(2)
	v_mfma_scale_f32_32x32x64_f8f6f4 v[98:113], v[222:229], v[146:153], v[230:245], v194, v193 op_sel_hi:[0,0,0]
	ds_read_b128 v[222:225], v213 offset:20480
	ds_read_b128 v[226:229], v214 offset:20480
	v_exp_f32_e32 v0, v90
	v_exp_f32_e32 v177, v91
	v_exp_f32_e32 v179, v92
	v_exp_f32_e32 v254, v93
	v_add_f32_e32 v219, v0, v219
	v_add_f32_e32 v219, v177, v219
	v_cvt_pk_fp8_f32 v248, v0, v177
	v_add_f32_e32 v219, v179, v219
	v_add_f32_e32 v219, v254, v219
	v_cvt_pk_fp8_f32 v248, v179, v254 op_sel:[0,0,1]
	v_exp_f32_e32 v0, v94
	v_exp_f32_e32 v177, v95
	v_exp_f32_e32 v179, v96
	v_exp_f32_e32 v254, v97
	v_add_f32_e32 v219, v0, v219
	v_add_f32_e32 v219, v177, v219
	v_cvt_pk_fp8_f32 v249, v0, v177
	v_add_f32_e32 v219, v179, v219
	v_add_f32_e32 v219, v254, v219
	v_cvt_pk_fp8_f32 v249, v179, v254 op_sel:[0,0,1]
	ds_read_b128 v[90:93], v185 offset:32768
	ds_read_b128 v[94:97], v186 offset:32768
	s_waitcnt lgkmcnt(4)
	v_mfma_scale_f32_32x32x64_f8f6f4 v[114:129], v[82:89], v[138:145], v[114:129], v194, v193 op_sel_hi:[0,0,0]
	v_exp_f32_e32 v0, v66
	v_exp_f32_e32 v177, v67
	v_exp_f32_e32 v179, v68
	v_exp_f32_e32 v254, v69
	v_add_f32_e32 v219, v0, v219
	v_add_f32_e32 v219, v177, v219
	v_cvt_pk_fp8_f32 v250, v0, v177
	v_add_f32_e32 v219, v179, v219
	v_add_f32_e32 v219, v254, v219
	v_cvt_pk_fp8_f32 v250, v179, v254 op_sel:[0,0,1]
	s_waitcnt lgkmcnt(2)
	v_mfma_scale_f32_32x32x64_f8f6f4 v[98:113], v[222:229], v[138:145], v[98:113], v194, v193 op_sel_hi:[0,0,0]
	ds_read_b128 v[222:225], v185 offset:34816
	ds_read_b128 v[226:229], v186 offset:34816
	v_exp_f32_e32 v0, v70
	v_exp_f32_e32 v177, v71
	v_exp_f32_e32 v179, v72
	v_exp_f32_e32 v254, v73
	v_add_f32_e32 v219, v0, v219
	v_add_f32_e32 v219, v177, v219
	v_cvt_pk_fp8_f32 v251, v0, v177
	v_add_f32_e32 v219, v179, v219
	v_add_f32_e32 v219, v254, v219
	v_cvt_pk_fp8_f32 v251, v179, v254 op_sel:[0,0,1]
	v_exp_f32_e32 v0, v74
	v_exp_f32_e32 v177, v75
	v_exp_f32_e32 v179, v76
	v_exp_f32_e32 v254, v77
	v_add_f32_e32 v219, v0, v219
	v_add_f32_e32 v219, v177, v219
	v_cvt_pk_fp8_f32 v252, v0, v177
	v_add_f32_e32 v219, v179, v219
	v_add_f32_e32 v219, v254, v219
	v_cvt_pk_fp8_f32 v252, v179, v254 op_sel:[0,0,1]
	s_waitcnt lgkmcnt(2)
	v_mfma_scale_f32_32x32x64_f8f6f4 v[114:129], v[90:97], v[130:137], v[114:129], v194, v193 op_sel_hi:[0,0,0]
	v_exp_f32_e32 v0, v78
	v_exp_f32_e32 v177, v79
	v_exp_f32_e32 v179, v80
	v_exp_f32_e32 v254, v81
	v_add_f32_e32 v219, v0, v219
	v_add_f32_e32 v219, v177, v219
	v_cvt_pk_fp8_f32 v253, v0, v177
	v_add_f32_e32 v219, v179, v219
	v_add_f32_e32 v219, v254, v219
	v_cvt_pk_fp8_f32 v253, v179, v254 op_sel:[0,0,1]
	ds_read_b128 v[90:93], v185 offset:43008
	ds_read_b128 v[94:97], v186 offset:43008
	ds_read_b128 v[82:85], v185 offset:45056
	ds_read_b128 v[86:89], v186 offset:45056
	ds_read_b128 v[74:77], v185 offset:47104
	ds_read_b128 v[78:81], v186 offset:47104
	ds_read_b128 v[66:69], v185 offset:49152
	ds_read_b128 v[70:73], v186 offset:49152
	s_waitcnt lgkmcnt(8)
	v_mfma_scale_f32_32x32x64_f8f6f4 v[98:113], v[222:229], v[130:137], v[98:113], v194, v193 op_sel_hi:[0,0,0]
	v_mov_b32_e32 v0, v219
	s_nop 1
	v_permlane32_swap_b32_e32 v219, v0
	v_add_f32_e32 v219, v219, v0
	v_fma_f32 v209, v209, v218, v219
	v_add_u32_e32 v176, 0x2000, v176
	v_add_u32_e32 v178, 0x20000, v178
	s_mov_b64 s[20:21], 0x1000
	v_lshl_add_u64 v[180:181], v[180:181], 0, s[20:21]
	v_max_f32_e32 v177, v114, v115
	v_max3_f32 v177, v177, v116, v117
	v_max3_f32 v177, v177, v118, v119
	v_max3_f32 v177, v177, v120, v121
	v_max3_f32 v177, v177, v122, v123
	v_max3_f32 v177, v177, v124, v125
	v_max3_f32 v177, v177, v126, v127
	v_max3_f32 v177, v177, v128, v129
	s_waitcnt lgkmcnt(6)
	v_mfma_scale_f32_32x32x64_f8f6f4 v[50:65], v[246:253], v[90:97], v[50:65], v194, v194 op_sel_hi:[0,0,0]
	v_max_f32_e32 v0, v98, v99
	v_max3_f32 v0, v0, v100, v101
	v_max3_f32 v0, v0, v102, v103
	s_waitcnt lgkmcnt(4)
	v_mfma_scale_f32_32x32x64_f8f6f4 v[34:49], v[246:253], v[82:89], v[34:49], v194, v194 op_sel_hi:[0,0,0]
	v_max3_f32 v0, v0, v104, v105
	v_max3_f32 v0, v0, v106, v107
	v_max3_f32 v0, v0, v108, v109
	s_waitcnt lgkmcnt(2)
	v_mfma_scale_f32_32x32x64_f8f6f4 v[18:33], v[246:253], v[74:81], v[18:33], v194, v194 op_sel_hi:[0,0,0]
	v_max3_f32 v0, v0, v110, v111
	v_max3_f32 v0, v0, v112, v113
	v_max_f32_e32 v177, v177, v0
	v_mov_b32_e32 v0, v177
	v_mov_b32_e32 v221, 1.0
	s_waitcnt vmcnt(0)
	ds_write_b128 v210, v[158:161] offset:8192
	ds_write_b128 v211, v[162:165] offset:24576
	ds_write_b128 v212, v[154:157] offset:36864
	s_waitcnt lgkmcnt(3)
	v_mfma_scale_f32_32x32x64_f8f6f4 v[2:17], v[246:253], v[66:73], v[2:17], v194, v194 op_sel_hi:[0,0,0]
	s_waitcnt lgkmcnt(0)
	s_barrier
	v_permlane32_swap_b32_e32 v177, v0
	v_max_f32_e32 v177, v177, v0
	v_cmp_ge_f32_e32 vcc, s90, v177
	s_cmp_eq_u64 vcc, exec
	s_cbranch_scc0 .Lmla_h2_newmax
; __device__ __forceinline__ void finishSM9(f32x16& p0, f32x16& p1, float alpha, float& l_reg, v8i32& p8) {
; #pragma unroll
;   for (int r = 0; r < 16; ++r) { p0[r] = __builtin_amdgcn_exp2f(p0[r]); p1[r] = __builtin_amdgcn_exp2f(p1[r]); }
;   float ps = 0;
; #pragma unroll
;   for (int r = 0; r < 16; ++r) ps += p0[r];
; #pragma unroll
;   for (int r = 0; r < 16; ++r) ps += p1[r];
;   { auto rr = __builtin_amdgcn_permlane32_swap(__float_as_uint(ps), __float_as_uint(ps), false, false);
;     ps = __uint_as_float(rr[0]) + __uint_as_float(rr[1]); }
;   l_reg = l_reg * alpha + ps;
; #pragma unroll
;   for (int g = 0; g < 4; ++g) {
;     int w = __builtin_amdgcn_cvt_pk_fp8_f32(p0[4 * g], p0[4 * g + 1], 0, false); p8[g] = __builtin_amdgcn_cvt_pk_fp8_f32(p0[4 * g + 2], p0[4 * g + 3], w, true);
;     int u = __builtin_amdgcn_cvt_pk_fp8_f32(p1[4 * g], p1[4 * g + 1], 0, false); p8[4 + g] = __builtin_amdgcn_cvt_pk_fp8_f32(p1[4 * g + 2], p1[4 * g + 3], u, true); }
; }
; __device__ __forceinline__ void pv8(f32x16* o, const char* Vt, const v8i32 p8, int r32, int hi) {
;   const int sw = (r32 >> 2) & 3, a0 = r32 * 64 + (((hi * 2) ^ sw) << 4), a1 = r32 * 64 + (((hi * 2 + 1) ^ sw) << 4);
; #pragma unroll
;   for (int d0 = 0; d0 < 4; ++d0) {
;     const v8i32 vf = cat8(*reinterpret_cast<const v4i32*>(Vt + d0 * 2048 + a0), *reinterpret_cast<const v4i32*>(Vt + d0 * 2048 + a1));
;     o[d0] = __builtin_amdgcn_mfma_scale_f32_32x32x64_f8f6f4(p8, vf, o[d0], 0, 0, 0, 127, 0, 127); }
; }
; __device__ __forceinline__ void qkt9(f32x16& p0, f32x16& p1, const char* Kn, const char* Kr, const v8i32* qf, const float init, int r32, int hi) {
; #pragma unroll
;   for (int r = 0; r < 16; ++r) { p0[r] = init; p1[r] = init; }
; #pragma unroll
;   for (int s = 0; s < 2; ++s) { const int c0 = s * 4 + hi * 2;
;     const v8i32 a0 = cat8(*reinterpret_cast<const v4i32*>(Kn + KN8SW(r32, c0)), *reinterpret_cast<const v4i32*>(Kn + KN8SW(r32, c0 + 1)));
;     const v8i32 a1 = cat8(*reinterpret_cast<const v4i32*>(Kn + 4096 + KN8SW(r32, c0)), *reinterpret_cast<const v4i32*>(Kn + 4096 + KN8SW(r32, c0 + 1)));
;     p0 = __builtin_amdgcn_mfma_scale_f32_32x32x64_f8f6f4(a0, qf[s], p0, 0, 0, 0, 127, 0, 124);
;     p1 = __builtin_amdgcn_mfma_scale_f32_32x32x64_f8f6f4(a1, qf[s], p1, 0, 0, 0, 127, 0, 124); }
;   { const int c0 = hi * 2;
.Lmla_h2_cont:
	global_load_dwordx4 v[158:161], v176, s[18:19]
	global_load_dwordx4 v[162:165], v178, s[16:17]
	global_load_dwordx4 v[154:157], v[180:181], off
	ds_read_b128 v[82:85], v215 offset:24576
	ds_read_b128 v[86:89], v216 offset:24576
	ds_read_b128 v[222:225], v215 offset:28672
	ds_read_b128 v[226:229], v216 offset:28672
	v_exp_f32_e32 v0, v114
	v_exp_f32_e32 v177, v115
	v_exp_f32_e32 v179, v116
	v_exp_f32_e32 v254, v117
	v_add_f32_e32 v219, v0, v177
	v_cvt_pk_fp8_f32 v246, v0, v177
	v_add_f32_e32 v219, v179, v219
	v_add_f32_e32 v219, v254, v219
	v_cvt_pk_fp8_f32 v246, v179, v254 op_sel:[0,0,1]
	s_waitcnt lgkmcnt(2)
	v_mfma_scale_f32_32x32x64_f8f6f4 v[82:97], v[82:89], v[146:153], v[230:245], v194, v193 op_sel_hi:[0,0,0]
	v_exp_f32_e32 v0, v118
	v_exp_f32_e32 v177, v119
	v_exp_f32_e32 v179, v120
	v_exp_f32_e32 v254, v121
	v_add_f32_e32 v219, v0, v219
	v_add_f32_e32 v219, v177, v219
	v_cvt_pk_fp8_f32 v247, v0, v177
	v_add_f32_e32 v219, v179, v219
	v_add_f32_e32 v219, v254, v219
	v_cvt_pk_fp8_f32 v247, v179, v254 op_sel:[0,0,1]
	ds_read_b128 v[114:117], v213 offset:24576
	ds_read_b128 v[118:121], v214 offset:24576
	s_waitcnt lgkmcnt(2)
	v_mfma_scale_f32_32x32x64_f8f6f4 v[66:81], v[222:229], v[146:153], v[230:245], v194, v193 op_sel_hi:[0,0,0]
	ds_read_b128 v[222:225], v213 offset:28672
	ds_read_b128 v[226:229], v214 offset:28672
	v_exp_f32_e32 v0, v122
	v_exp_f32_e32 v177, v123
	v_exp_f32_e32 v179, v124
	v_exp_f32_e32 v254, v125
	v_add_f32_e32 v219, v0, v219
	v_add_f32_e32 v219, v177, v219
	v_cvt_pk_fp8_f32 v248, v0, v177
	v_add_f32_e32 v219, v179, v219
	v_add_f32_e32 v219, v254, v219
	v_cvt_pk_fp8_f32 v248, v179, v254 op_sel:[0,0,1]
	v_exp_f32_e32 v0, v126
	v_exp_f32_e32 v177, v127
	v_exp_f32_e32 v179, v128
	v_exp_f32_e32 v254, v129
	v_add_f32_e32 v219, v0, v219
	v_add_f32_e32 v219, v177, v219
	v_cvt_pk_fp8_f32 v249, v0, v177
	v_add_f32_e32 v219, v179, v219
	v_add_f32_e32 v219, v254, v219
	v_cvt_pk_fp8_f32 v249, v179, v254 op_sel:[0,0,1]
	ds_read_b128 v[122:125], v185 offset:36864
	ds_read_b128 v[126:129], v186 offset:36864
	s_waitcnt lgkmcnt(4)
	v_mfma_scale_f32_32x32x64_f8f6f4 v[82:97], v[114:121], v[138:145], v[82:97], v194, v193 op_sel_hi:[0,0,0]
	v_exp_f32_e32 v0, v98
	v_exp_f32_e32 v177, v99
	v_exp_f32_e32 v179, v100
	v_exp_f32_e32 v254, v101
	v_add_f32_e32 v219, v0, v219
	v_add_f32_e32 v219, v177, v219
	v_cvt_pk_fp8_f32 v250, v0, v177
	v_add_f32_e32 v219, v179, v219
	v_add_f32_e32 v219, v254, v219
	v_cvt_pk_fp8_f32 v250, v179, v254 op_sel:[0,0,1]
	s_waitcnt lgkmcnt(2)
	v_mfma_scale_f32_32x32x64_f8f6f4 v[66:81], v[222:229], v[138:145], v[66:81], v194, v193 op_sel_hi:[0,0,0]
	ds_read_b128 v[222:225], v185 offset:38912
	ds_read_b128 v[226:229], v186 offset:38912
	v_exp_f32_e32 v0, v102
	v_exp_f32_e32 v177, v103
	v_exp_f32_e32 v179, v104
	v_exp_f32_e32 v254, v105
	v_add_f32_e32 v219, v0, v219
	v_add_f32_e32 v219, v177, v219
	v_cvt_pk_fp8_f32 v251, v0, v177
	v_add_f32_e32 v219, v179, v219
	v_add_f32_e32 v219, v254, v219
	v_cvt_pk_fp8_f32 v251, v179, v254 op_sel:[0,0,1]
	v_exp_f32_e32 v0, v106
	v_exp_f32_e32 v177, v107
	v_exp_f32_e32 v179, v108
	v_exp_f32_e32 v254, v109
	v_add_f32_e32 v219, v0, v219
	v_add_f32_e32 v219, v177, v219
	v_cvt_pk_fp8_f32 v252, v0, v177
	v_add_f32_e32 v219, v179, v219
	v_add_f32_e32 v219, v254, v219
	v_cvt_pk_fp8_f32 v252, v179, v254 op_sel:[0,0,1]
	s_waitcnt lgkmcnt(2)
	v_mfma_scale_f32_32x32x64_f8f6f4 v[82:97], v[122:129], v[130:137], v[82:97], v194, v193 op_sel_hi:[0,0,0]
	v_exp_f32_e32 v0, v110
	v_exp_f32_e32 v177, v111
	v_exp_f32_e32 v179, v112
	v_exp_f32_e32 v254, v113
	v_add_f32_e32 v219, v0, v219
	v_add_f32_e32 v219, v177, v219
	v_cvt_pk_fp8_f32 v253, v0, v177
	v_add_f32_e32 v219, v179, v219
	v_add_f32_e32 v219, v254, v219
	v_cvt_pk_fp8_f32 v253, v179, v254 op_sel:[0,0,1]
	ds_read_b128 v[122:125], v185 offset:0
	ds_read_b128 v[126:129], v186 offset:0
	ds_read_b128 v[114:117], v185 offset:2048
	ds_read_b128 v[118:121], v186 offset:2048
	ds_read_b128 v[106:109], v185 offset:4096
	ds_read_b128 v[110:113], v186 offset:4096
	ds_read_b128 v[98:101], v185 offset:6144
	ds_read_b128 v[102:105], v186 offset:6144
	s_waitcnt lgkmcnt(8)
	v_mfma_scale_f32_32x32x64_f8f6f4 v[66:81], v[222:229], v[130:137], v[66:81], v194, v193 op_sel_hi:[0,0,0]
	v_mov_b32_e32 v0, v219
	s_nop 1
	v_permlane32_swap_b32_e32 v219, v0
	v_add_f32_e32 v219, v219, v0
	v_fma_f32 v209, v209, v221, v219
	v_add_u32_e32 v176, 0x2000, v176
	v_add_u32_e32 v178, 0x20000, v178
	s_mov_b64 s[20:21], 0x1000
	v_lshl_add_u64 v[180:181], v[180:181], 0, s[20:21]
	v_max_f32_e32 v177, v82, v83
	v_max3_f32 v177, v177, v84, v85
	v_max3_f32 v177, v177, v86, v87
	v_max3_f32 v177, v177, v88, v89
	v_max3_f32 v177, v177, v90, v91
	v_max3_f32 v177, v177, v92, v93
	v_max3_f32 v177, v177, v94, v95
	v_max3_f32 v177, v177, v96, v97
	s_waitcnt lgkmcnt(6)
	v_mfma_scale_f32_32x32x64_f8f6f4 v[50:65], v[246:253], v[122:129], v[50:65], v194, v194 op_sel_hi:[0,0,0]
	v_max_f32_e32 v0, v66, v67
	v_max3_f32 v0, v0, v68, v69
	v_max3_f32 v0, v0, v70, v71
	s_waitcnt lgkmcnt(4)
	v_mfma_scale_f32_32x32x64_f8f6f4 v[34:49], v[246:253], v[114:121], v[34:49], v194, v194 op_sel_hi:[0,0,0]
	v_max3_f32 v0, v0, v72, v73
	v_max3_f32 v0, v0, v74, v75
	v_max3_f32 v0, v0, v76, v77
	s_waitcnt lgkmcnt(2)
	v_mfma_scale_f32_32x32x64_f8f6f4 v[18:33], v[246:253], v[106:113], v[18:33], v194, v194 op_sel_hi:[0,0,0]
	v_max3_f32 v0, v0, v78, v79
	v_max3_f32 v0, v0, v80, v81
	v_max_f32_e32 v177, v177, v0
	v_mov_b32_e32 v0, v177
	v_mov_b32_e32 v218, 1.0
	s_waitcnt vmcnt(0)
	ds_write_b128 v210, v[158:161] offset:43008
	ds_write_b128 v211, v[162:165] offset:51200
	ds_write_b128 v212, v[154:157] offset:59392
	s_waitcnt lgkmcnt(3)
	v_mfma_scale_f32_32x32x64_f8f6f4 v[2:17], v[246:253], v[98:105], v[2:17], v194, v194 op_sel_hi:[0,0,0]
	s_waitcnt lgkmcnt(0)
	s_barrier
	v_permlane32_swap_b32_e32 v177, v0
	v_max_f32_e32 v177, v177, v0
	v_cmp_ge_f32_e32 vcc, s90, v177
	s_cmp_eq_u64 vcc, exec
	s_cbranch_scc0 .Lmla_h3_newmax
; __device__ __forceinline__ void finishSM9(f32x16& p0, f32x16& p1, float alpha, float& l_reg, v8i32& p8) {
; #pragma unroll
;   for (int r = 0; r < 16; ++r) { p0[r] = __builtin_amdgcn_exp2f(p0[r]); p1[r] = __builtin_amdgcn_exp2f(p1[r]); }
;   float ps = 0;
; #pragma unroll
;   for (int r = 0; r < 16; ++r) ps += p0[r];
; #pragma unroll
;   for (int r = 0; r < 16; ++r) ps += p1[r];
;   { auto rr = __builtin_amdgcn_permlane32_swap(__float_as_uint(ps), __float_as_uint(ps), false, false);
;     ps = __uint_as_float(rr[0]) + __uint_as_float(rr[1]); }
;   l_reg = l_reg * alpha + ps;
; #pragma unroll
;   for (int g = 0; g < 4; ++g) {
;     int w = __builtin_amdgcn_cvt_pk_fp8_f32(p0[4 * g], p0[4 * g + 1], 0, false); p8[g] = __builtin_amdgcn_cvt_pk_fp8_f32(p0[4 * g + 2], p0[4 * g + 3], w, true);
;     int u = __builtin_amdgcn_cvt_pk_fp8_f32(p1[4 * g], p1[4 * g + 1], 0, false); p8[4 + g] = __builtin_amdgcn_cvt_pk_fp8_f32(p1[4 * g + 2], p1[4 * g + 3], u, true); }
; }
; __device__ __forceinline__ void pv8(f32x16* o, const char* Vt, const v8i32 p8, int r32, int hi) {
;   const int sw = (r32 >> 2) & 3, a0 = r32 * 64 + (((hi * 2) ^ sw) << 4), a1 = r32 * 64 + (((hi * 2 + 1) ^ sw) << 4);
; #pragma unroll
;   for (int d0 = 0; d0 < 4; ++d0) {
;     const v8i32 vf = cat8(*reinterpret_cast<const v4i32*>(Vt + d0 * 2048 + a0), *reinterpret_cast<const v4i32*>(Vt + d0 * 2048 + a1));
;     o[d0] = __builtin_amdgcn_mfma_scale_f32_32x32x64_f8f6f4(p8, vf, o[d0], 0, 0, 0, 127, 0, 127); }
; }
; __device__ __forceinline__ void qkt9(f32x16& p0, f32x16& p1, const char* Kn, const char* Kr, const v8i32* qf, const float init, int r32, int hi) {
; #pragma unroll
;   for (int r = 0; r < 16; ++r) { p0[r] = init; p1[r] = init; }
; #pragma unroll
;   for (int s = 0; s < 2; ++s) { const int c0 = s * 4 + hi * 2;
;     const v8i32 a0 = cat8(*reinterpret_cast<const v4i32*>(Kn + KN8SW(r32, c0)), *reinterpret_cast<const v4i32*>(Kn + KN8SW(r32, c0 + 1)));
;     const v8i32 a1 = cat8(*reinterpret_cast<const v4i32*>(Kn + 4096 + KN8SW(r32, c0)), *reinterpret_cast<const v4i32*>(Kn + 4096 + KN8SW(r32, c0 + 1)));
;     p0 = __builtin_amdgcn_mfma_scale_f32_32x32x64_f8f6f4(a0, qf[s], p0, 0, 0, 0, 127, 0, 124);
;     p1 = __builtin_amdgcn_mfma_scale_f32_32x32x64_f8f6f4(a1, qf[s], p1, 0, 0, 0, 127, 0, 124); }
;   { const int c0 = hi * 2;
.Lmla_h3_cont:
	global_load_dwordx4 v[158:161], v176, s[18:19]
	global_load_dwordx4 v[162:165], v178, s[16:17]
	global_load_dwordx4 v[154:157], v[180:181], off
	ds_read_b128 v[114:117], v215 offset:51200
	ds_read_b128 v[118:121], v216 offset:51200
	ds_read_b128 v[222:225], v215 offset:55296
	ds_read_b128 v[226:229], v216 offset:55296
	v_exp_f32_e32 v0, v82
	v_exp_f32_e32 v177, v83
	v_exp_f32_e32 v179, v84
	v_exp_f32_e32 v254, v85
	v_add_f32_e32 v219, v0, v177
	v_cvt_pk_fp8_f32 v246, v0, v177
	v_add_f32_e32 v219, v179, v219
	v_add_f32_e32 v219, v254, v219
	v_cvt_pk_fp8_f32 v246, v179, v254 op_sel:[0,0,1]
	s_waitcnt lgkmcnt(2)
	v_mfma_scale_f32_32x32x64_f8f6f4 v[114:129], v[114:121], v[146:153], v[230:245], v194, v193 op_sel_hi:[0,0,0]
	v_exp_f32_e32 v0, v86
	v_exp_f32_e32 v177, v87
	v_exp_f32_e32 v179, v88
	v_exp_f32_e32 v254, v89
	v_add_f32_e32 v219, v0, v219
	v_add_f32_e32 v219, v177, v219
	v_cvt_pk_fp8_f32 v247, v0, v177
	v_add_f32_e32 v219, v179, v219
	v_add_f32_e32 v219, v254, v219
	v_cvt_pk_fp8_f32 v247, v179, v254 op_sel:[0,0,1]
	ds_read_b128 v[82:85], v213 offset:51200
	ds_read_b128 v[86:89], v214 offset:51200
	s_waitcnt lgkmcnt(2)
	v_mfma_scale_f32_32x32x64_f8f6f4 v[98:113], v[222:229], v[146:153], v[230:245], v194, v193 op_sel_hi:[0,0,0]
	ds_read_b128 v[222:225], v213 offset:55296
	ds_read_b128 v[226:229], v214 offset:55296
	v_exp_f32_e32 v0, v90
	v_exp_f32_e32 v177, v91
	v_exp_f32_e32 v179, v92
	v_exp_f32_e32 v254, v93
	v_add_f32_e32 v219, v0, v219
	v_add_f32_e32 v219, v177, v219
	v_cvt_pk_fp8_f32 v248, v0, v177
	v_add_f32_e32 v219, v179, v219
	v_add_f32_e32 v219, v254, v219
	v_cvt_pk_fp8_f32 v248, v179, v254 op_sel:[0,0,1]
	v_exp_f32_e32 v0, v94
	v_exp_f32_e32 v177, v95
	v_exp_f32_e32 v179, v96
	v_exp_f32_e32 v254, v97
	v_add_f32_e32 v219, v0, v219
	v_add_f32_e32 v219, v177, v219
	v_cvt_pk_fp8_f32 v249, v0, v177
	v_add_f32_e32 v219, v179, v219
	v_add_f32_e32 v219, v254, v219
	v_cvt_pk_fp8_f32 v249, v179, v254 op_sel:[0,0,1]
	ds_read_b128 v[90:93], v185 offset:59392
	ds_read_b128 v[94:97], v186 offset:59392
	s_waitcnt lgkmcnt(4)
	v_mfma_scale_f32_32x32x64_f8f6f4 v[114:129], v[82:89], v[138:145], v[114:129], v194, v193 op_sel_hi:[0,0,0]
	v_exp_f32_e32 v0, v66
	v_exp_f32_e32 v177, v67
	v_exp_f32_e32 v179, v68
	v_exp_f32_e32 v254, v69
	v_add_f32_e32 v219, v0, v219
	v_add_f32_e32 v219, v177, v219
	v_cvt_pk_fp8_f32 v250, v0, v177
	v_add_f32_e32 v219, v179, v219
	v_add_f32_e32 v219, v254, v219
	v_cvt_pk_fp8_f32 v250, v179, v254 op_sel:[0,0,1]
	s_waitcnt lgkmcnt(2)
	v_mfma_scale_f32_32x32x64_f8f6f4 v[98:113], v[222:229], v[138:145], v[98:113], v194, v193 op_sel_hi:[0,0,0]
	ds_read_b128 v[222:225], v185 offset:61440
	ds_read_b128 v[226:229], v186 offset:61440
	v_exp_f32_e32 v0, v70
	v_exp_f32_e32 v177, v71
	v_exp_f32_e32 v179, v72
	v_exp_f32_e32 v254, v73
	v_add_f32_e32 v219, v0, v219
	v_add_f32_e32 v219, v177, v219
	v_cvt_pk_fp8_f32 v251, v0, v177
	v_add_f32_e32 v219, v179, v219
	v_add_f32_e32 v219, v254, v219
	v_cvt_pk_fp8_f32 v251, v179, v254 op_sel:[0,0,1]
	v_exp_f32_e32 v0, v74
	v_exp_f32_e32 v177, v75
	v_exp_f32_e32 v179, v76
	v_exp_f32_e32 v254, v77
	v_add_f32_e32 v219, v0, v219
	v_add_f32_e32 v219, v177, v219
	v_cvt_pk_fp8_f32 v252, v0, v177
	v_add_f32_e32 v219, v179, v219
	v_add_f32_e32 v219, v254, v219
	v_cvt_pk_fp8_f32 v252, v179, v254 op_sel:[0,0,1]
	s_waitcnt lgkmcnt(2)
	v_mfma_scale_f32_32x32x64_f8f6f4 v[114:129], v[90:97], v[130:137], v[114:129], v194, v193 op_sel_hi:[0,0,0]
	v_exp_f32_e32 v0, v78
	v_exp_f32_e32 v177, v79
	v_exp_f32_e32 v179, v80
	v_exp_f32_e32 v254, v81
	v_add_f32_e32 v219, v0, v219
	v_add_f32_e32 v219, v177, v219
	v_cvt_pk_fp8_f32 v253, v0, v177
	v_add_f32_e32 v219, v179, v219
	v_add_f32_e32 v219, v254, v219
	v_cvt_pk_fp8_f32 v253, v179, v254 op_sel:[0,0,1]
	ds_read_b128 v[90:93], v185 offset:8192
	ds_read_b128 v[94:97], v186 offset:8192
	ds_read_b128 v[82:85], v185 offset:10240
	ds_read_b128 v[86:89], v186 offset:10240
	ds_read_b128 v[74:77], v185 offset:12288
	ds_read_b128 v[78:81], v186 offset:12288
	ds_read_b128 v[66:69], v185 offset:14336
	ds_read_b128 v[70:73], v186 offset:14336
	s_waitcnt lgkmcnt(8)
	v_mfma_scale_f32_32x32x64_f8f6f4 v[98:113], v[222:229], v[130:137], v[98:113], v194, v193 op_sel_hi:[0,0,0]
	v_mov_b32_e32 v0, v219
	s_nop 1
	v_permlane32_swap_b32_e32 v219, v0
	v_add_f32_e32 v219, v219, v0
	v_fma_f32 v209, v209, v218, v219
	v_add_u32_e32 v176, 0x2000, v176
	v_add_u32_e32 v178, 0x20000, v178
	s_mov_b64 s[20:21], 0x1000
	v_lshl_add_u64 v[180:181], v[180:181], 0, s[20:21]
	v_max_f32_e32 v177, v114, v115
	v_max3_f32 v177, v177, v116, v117
	v_max3_f32 v177, v177, v118, v119
	v_max3_f32 v177, v177, v120, v121
	v_max3_f32 v177, v177, v122, v123
	v_max3_f32 v177, v177, v124, v125
	v_max3_f32 v177, v177, v126, v127
	v_max3_f32 v177, v177, v128, v129
	s_waitcnt lgkmcnt(6)
	v_mfma_scale_f32_32x32x64_f8f6f4 v[50:65], v[246:253], v[90:97], v[50:65], v194, v194 op_sel_hi:[0,0,0]
	v_max_f32_e32 v0, v98, v99
	v_max3_f32 v0, v0, v100, v101
	v_max3_f32 v0, v0, v102, v103
	s_waitcnt lgkmcnt(4)
	v_mfma_scale_f32_32x32x64_f8f6f4 v[34:49], v[246:253], v[82:89], v[34:49], v194, v194 op_sel_hi:[0,0,0]
	v_max3_f32 v0, v0, v104, v105
	v_max3_f32 v0, v0, v106, v107
	v_max3_f32 v0, v0, v108, v109
	s_waitcnt lgkmcnt(2)
	v_mfma_scale_f32_32x32x64_f8f6f4 v[18:33], v[246:253], v[74:81], v[18:33], v194, v194 op_sel_hi:[0,0,0]
	v_max3_f32 v0, v0, v110, v111
	v_max3_f32 v0, v0, v112, v113
	v_max_f32_e32 v177, v177, v0
	v_mov_b32_e32 v0, v177
	v_mov_b32_e32 v221, 1.0
	s_waitcnt vmcnt(0)
	ds_write_b128 v210, v[158:161]
	ds_write_b128 v211, v[162:165] offset:16384
	ds_write_b128 v212, v[154:157] offset:32768
	s_waitcnt lgkmcnt(3)
	v_mfma_scale_f32_32x32x64_f8f6f4 v[2:17], v[246:253], v[66:73], v[2:17], v194, v194 op_sel_hi:[0,0,0]
	s_waitcnt lgkmcnt(0)
	s_barrier
	v_permlane32_swap_b32_e32 v177, v0
	v_max_f32_e32 v177, v177, v0
	v_cmp_ge_f32_e32 vcc, s90, v177
	s_cmp_eq_u64 vcc, exec
	s_cbranch_scc0 .Lmla_h4_newmax
; __device__ __forceinline__ void finishSM9(f32x16& p0, f32x16& p1, float alpha, float& l_reg, v8i32& p8) {
; #pragma unroll
;   for (int r = 0; r < 16; ++r) { p0[r] = __builtin_amdgcn_exp2f(p0[r]); p1[r] = __builtin_amdgcn_exp2f(p1[r]); }
;   float ps = 0;
; #pragma unroll
;   for (int r = 0; r < 16; ++r) ps += p0[r];
; #pragma unroll
;   for (int r = 0; r < 16; ++r) ps += p1[r];
;   { auto rr = __builtin_amdgcn_permlane32_swap(__float_as_uint(ps), __float_as_uint(ps), false, false);
;     ps = __uint_as_float(rr[0]) + __uint_as_float(rr[1]); }
;   l_reg = l_reg * alpha + ps;
; #pragma unroll
;   for (int g = 0; g < 4; ++g) {
;     int w = __builtin_amdgcn_cvt_pk_fp8_f32(p0[4 * g], p0[4 * g + 1], 0, false); p8[g] = __builtin_amdgcn_cvt_pk_fp8_f32(p0[4 * g + 2], p0[4 * g + 3], w, true);
;     int u = __builtin_amdgcn_cvt_pk_fp8_f32(p1[4 * g], p1[4 * g + 1], 0, false); p8[4 + g] = __builtin_amdgcn_cvt_pk_fp8_f32(p1[4 * g + 2], p1[4 * g + 3], u, true); }
; }
; __device__ __forceinline__ void pv8(f32x16* o, const char* Vt, const v8i32 p8, int r32, int hi) {
;   const int sw = (r32 >> 2) & 3, a0 = r32 * 64 + (((hi * 2) ^ sw) << 4), a1 = r32 * 64 + (((hi * 2 + 1) ^ sw) << 4);
; #pragma unroll
;   for (int d0 = 0; d0 < 4; ++d0) {
;     const v8i32 vf = cat8(*reinterpret_cast<const v4i32*>(Vt + d0 * 2048 + a0), *reinterpret_cast<const v4i32*>(Vt + d0 * 2048 + a1));
;     o[d0] = __builtin_amdgcn_mfma_scale_f32_32x32x64_f8f6f4(p8, vf, o[d0], 0, 0, 0, 127, 0, 127); }
; }
; __device__ __forceinline__ void qkt9(f32x16& p0, f32x16& p1, const char* Kn, const char* Kr, const v8i32* qf, const float init, int r32, int hi) {
; #pragma unroll
;   for (int r = 0; r < 16; ++r) { p0[r] = init; p1[r] = init; }
; #pragma unroll
;   for (int s = 0; s < 2; ++s) { const int c0 = s * 4 + hi * 2;
;     const v8i32 a0 = cat8(*reinterpret_cast<const v4i32*>(Kn + KN8SW(r32, c0)), *reinterpret_cast<const v4i32*>(Kn + KN8SW(r32, c0 + 1)));
;     const v8i32 a1 = cat8(*reinterpret_cast<const v4i32*>(Kn + 4096 + KN8SW(r32, c0)), *reinterpret_cast<const v4i32*>(Kn + 4096 + KN8SW(r32, c0 + 1)));
;     p0 = __builtin_amdgcn_mfma_scale_f32_32x32x64_f8f6f4(a0, qf[s], p0, 0, 0, 0, 127, 0, 124);
;     p1 = __builtin_amdgcn_mfma_scale_f32_32x32x64_f8f6f4(a1, qf[s], p1, 0, 0, 0, 127, 0, 124); }
;   { const int c0 = hi * 2;
.Lmla_h4_cont:
	global_load_dwordx4 v[158:161], v176, s[18:19]
	global_load_dwordx4 v[162:165], v178, s[16:17]
	global_load_dwordx4 v[154:157], v[180:181], off
	ds_read_b128 v[82:85], v215 offset:16384
	ds_read_b128 v[86:89], v216 offset:16384
	ds_read_b128 v[222:225], v215 offset:20480
	ds_read_b128 v[226:229], v216 offset:20480
	v_exp_f32_e32 v0, v114
	v_exp_f32_e32 v177, v115
	v_exp_f32_e32 v179, v116
	v_exp_f32_e32 v254, v117
	v_add_f32_e32 v219, v0, v177
	v_cvt_pk_fp8_f32 v246, v0, v177
	v_add_f32_e32 v219, v179, v219
	v_add_f32_e32 v219, v254, v219
	v_cvt_pk_fp8_f32 v246, v179, v254 op_sel:[0,0,1]
	s_waitcnt lgkmcnt(2)
	v_mfma_scale_f32_32x32x64_f8f6f4 v[82:97], v[82:89], v[146:153], v[230:245], v194, v193 op_sel_hi:[0,0,0]
	v_exp_f32_e32 v0, v118
	v_exp_f32_e32 v177, v119
	v_exp_f32_e32 v179, v120
	v_exp_f32_e32 v254, v121
	v_add_f32_e32 v219, v0, v219
	v_add_f32_e32 v219, v177, v219
	v_cvt_pk_fp8_f32 v247, v0, v177
	v_add_f32_e32 v219, v179, v219
	v_add_f32_e32 v219, v254, v219
	v_cvt_pk_fp8_f32 v247, v179, v254 op_sel:[0,0,1]
	ds_read_b128 v[114:117], v213 offset:16384
	ds_read_b128 v[118:121], v214 offset:16384
	s_waitcnt lgkmcnt(2)
	v_mfma_scale_f32_32x32x64_f8f6f4 v[66:81], v[222:229], v[146:153], v[230:245], v194, v193 op_sel_hi:[0,0,0]
	ds_read_b128 v[222:225], v213 offset:20480
	ds_read_b128 v[226:229], v214 offset:20480
	v_exp_f32_e32 v0, v122
	v_exp_f32_e32 v177, v123
	v_exp_f32_e32 v179, v124
	v_exp_f32_e32 v254, v125
	v_add_f32_e32 v219, v0, v219
	v_add_f32_e32 v219, v177, v219
	v_cvt_pk_fp8_f32 v248, v0, v177
	v_add_f32_e32 v219, v179, v219
	v_add_f32_e32 v219, v254, v219
	v_cvt_pk_fp8_f32 v248, v179, v254 op_sel:[0,0,1]
	v_exp_f32_e32 v0, v126
	v_exp_f32_e32 v177, v127
	v_exp_f32_e32 v179, v128
	v_exp_f32_e32 v254, v129
	v_add_f32_e32 v219, v0, v219
	v_add_f32_e32 v219, v177, v219
	v_cvt_pk_fp8_f32 v249, v0, v177
	v_add_f32_e32 v219, v179, v219
	v_add_f32_e32 v219, v254, v219
	v_cvt_pk_fp8_f32 v249, v179, v254 op_sel:[0,0,1]
	ds_read_b128 v[122:125], v185 offset:32768
	ds_read_b128 v[126:129], v186 offset:32768
	s_waitcnt lgkmcnt(4)
	v_mfma_scale_f32_32x32x64_f8f6f4 v[82:97], v[114:121], v[138:145], v[82:97], v194, v193 op_sel_hi:[0,0,0]
	v_exp_f32_e32 v0, v98
	v_exp_f32_e32 v177, v99
	v_exp_f32_e32 v179, v100
	v_exp_f32_e32 v254, v101
	v_add_f32_e32 v219, v0, v219
	v_add_f32_e32 v219, v177, v219
	v_cvt_pk_fp8_f32 v250, v0, v177
	v_add_f32_e32 v219, v179, v219
	v_add_f32_e32 v219, v254, v219
	v_cvt_pk_fp8_f32 v250, v179, v254 op_sel:[0,0,1]
	s_waitcnt lgkmcnt(2)
	v_mfma_scale_f32_32x32x64_f8f6f4 v[66:81], v[222:229], v[138:145], v[66:81], v194, v193 op_sel_hi:[0,0,0]
	ds_read_b128 v[222:225], v185 offset:34816
	ds_read_b128 v[226:229], v186 offset:34816
	v_exp_f32_e32 v0, v102
	v_exp_f32_e32 v177, v103
	v_exp_f32_e32 v179, v104
	v_exp_f32_e32 v254, v105
	v_add_f32_e32 v219, v0, v219
	v_add_f32_e32 v219, v177, v219
	v_cvt_pk_fp8_f32 v251, v0, v177
	v_add_f32_e32 v219, v179, v219
	v_add_f32_e32 v219, v254, v219
	v_cvt_pk_fp8_f32 v251, v179, v254 op_sel:[0,0,1]
	v_exp_f32_e32 v0, v106
	v_exp_f32_e32 v177, v107
	v_exp_f32_e32 v179, v108
	v_exp_f32_e32 v254, v109
	v_add_f32_e32 v219, v0, v219
	v_add_f32_e32 v219, v177, v219
	v_cvt_pk_fp8_f32 v252, v0, v177
	v_add_f32_e32 v219, v179, v219
	v_add_f32_e32 v219, v254, v219
	v_cvt_pk_fp8_f32 v252, v179, v254 op_sel:[0,0,1]
	s_waitcnt lgkmcnt(2)
	v_mfma_scale_f32_32x32x64_f8f6f4 v[82:97], v[122:129], v[130:137], v[82:97], v194, v193 op_sel_hi:[0,0,0]
	v_exp_f32_e32 v0, v110
	v_exp_f32_e32 v177, v111
	v_exp_f32_e32 v179, v112
	v_exp_f32_e32 v254, v113
	v_add_f32_e32 v219, v0, v219
	v_add_f32_e32 v219, v177, v219
	v_cvt_pk_fp8_f32 v253, v0, v177
	v_add_f32_e32 v219, v179, v219
	v_add_f32_e32 v219, v254, v219
	v_cvt_pk_fp8_f32 v253, v179, v254 op_sel:[0,0,1]
	ds_read_b128 v[122:125], v185 offset:43008
	ds_read_b128 v[126:129], v186 offset:43008
	ds_read_b128 v[114:117], v185 offset:45056
	ds_read_b128 v[118:121], v186 offset:45056
	ds_read_b128 v[106:109], v185 offset:47104
	ds_read_b128 v[110:113], v186 offset:47104
	ds_read_b128 v[98:101], v185 offset:49152
	ds_read_b128 v[102:105], v186 offset:49152
	s_waitcnt lgkmcnt(8)
	v_mfma_scale_f32_32x32x64_f8f6f4 v[66:81], v[222:229], v[130:137], v[66:81], v194, v193 op_sel_hi:[0,0,0]
	v_mov_b32_e32 v0, v219
	s_nop 1
	v_permlane32_swap_b32_e32 v219, v0
	v_add_f32_e32 v219, v219, v0
	v_fma_f32 v209, v209, v221, v219
	v_add_u32_e32 v176, 0x2000, v176
	v_add_u32_e32 v178, 0x20000, v178
	s_mov_b64 s[20:21], 0x1000
	v_lshl_add_u64 v[180:181], v[180:181], 0, s[20:21]
	v_max_f32_e32 v177, v82, v83
	v_max3_f32 v177, v177, v84, v85
	v_max3_f32 v177, v177, v86, v87
	v_max3_f32 v177, v177, v88, v89
	v_max3_f32 v177, v177, v90, v91
	v_max3_f32 v177, v177, v92, v93
	v_max3_f32 v177, v177, v94, v95
	v_max3_f32 v177, v177, v96, v97
	s_waitcnt lgkmcnt(6)
	v_mfma_scale_f32_32x32x64_f8f6f4 v[50:65], v[246:253], v[122:129], v[50:65], v194, v194 op_sel_hi:[0,0,0]
	v_max_f32_e32 v0, v66, v67
	v_max3_f32 v0, v0, v68, v69
	v_max3_f32 v0, v0, v70, v71
	s_waitcnt lgkmcnt(4)
	v_mfma_scale_f32_32x32x64_f8f6f4 v[34:49], v[246:253], v[114:121], v[34:49], v194, v194 op_sel_hi:[0,0,0]
	v_max3_f32 v0, v0, v72, v73
	v_max3_f32 v0, v0, v74, v75
	v_max3_f32 v0, v0, v76, v77
	s_waitcnt lgkmcnt(2)
	v_mfma_scale_f32_32x32x64_f8f6f4 v[18:33], v[246:253], v[106:113], v[18:33], v194, v194 op_sel_hi:[0,0,0]
	v_max3_f32 v0, v0, v78, v79
	v_max3_f32 v0, v0, v80, v81
	v_max_f32_e32 v177, v177, v0
	v_mov_b32_e32 v0, v177
	v_mov_b32_e32 v218, 1.0
	s_waitcnt vmcnt(0)
	ds_write_b128 v210, v[158:161] offset:8192
	ds_write_b128 v211, v[162:165] offset:24576
	ds_write_b128 v212, v[154:157] offset:36864
	s_waitcnt lgkmcnt(3)
	v_mfma_scale_f32_32x32x64_f8f6f4 v[2:17], v[246:253], v[98:105], v[2:17], v194, v194 op_sel_hi:[0,0,0]
	s_waitcnt lgkmcnt(0)
	s_barrier
	v_permlane32_swap_b32_e32 v177, v0
	v_max_f32_e32 v177, v177, v0
	v_cmp_ge_f32_e32 vcc, s90, v177
	s_cmp_eq_u64 vcc, exec
	s_cbranch_scc0 .Lmla_h5_newmax
; __device__ __forceinline__ void finishSM9(f32x16& p0, f32x16& p1, float alpha, float& l_reg, v8i32& p8) {
; #pragma unroll
;   for (int r = 0; r < 16; ++r) { p0[r] = __builtin_amdgcn_exp2f(p0[r]); p1[r] = __builtin_amdgcn_exp2f(p1[r]); }
;   float ps = 0;
; #pragma unroll
;   for (int r = 0; r < 16; ++r) ps += p0[r];
; #pragma unroll
;   for (int r = 0; r < 16; ++r) ps += p1[r];
;   { auto rr = __builtin_amdgcn_permlane32_swap(__float_as_uint(ps), __float_as_uint(ps), false, false);
;     ps = __uint_as_float(rr[0]) + __uint_as_float(rr[1]); }
;   l_reg = l_reg * alpha + ps;
; #pragma unroll
;   for (int g = 0; g < 4; ++g) {
;     int w = __builtin_amdgcn_cvt_pk_fp8_f32(p0[4 * g], p0[4 * g + 1], 0, false); p8[g] = __builtin_amdgcn_cvt_pk_fp8_f32(p0[4 * g + 2], p0[4 * g + 3], w, true);
;     int u = __builtin_amdgcn_cvt_pk_fp8_f32(p1[4 * g], p1[4 * g + 1], 0, false); p8[4 + g] = __builtin_amdgcn_cvt_pk_fp8_f32(p1[4 * g + 2], p1[4 * g + 3], u, true); }
; }
; __device__ __forceinline__ void pv8(f32x16* o, const char* Vt, const v8i32 p8, int r32, int hi) {
;   const int sw = (r32 >> 2) & 3, a0 = r32 * 64 + (((hi * 2) ^ sw) << 4), a1 = r32 * 64 + (((hi * 2 + 1) ^ sw) << 4);
; #pragma unroll
;   for (int d0 = 0; d0 < 4; ++d0) {
;     const v8i32 vf = cat8(*reinterpret_cast<const v4i32*>(Vt + d0 * 2048 + a0), *reinterpret_cast<const v4i32*>(Vt + d0 * 2048 + a1));
;     o[d0] = __builtin_amdgcn_mfma_scale_f32_32x32x64_f8f6f4(p8, vf, o[d0], 0, 0, 0, 127, 0, 127); }
; }
; __device__ __forceinline__ void qkt9(f32x16& p0, f32x16& p1, const char* Kn, const char* Kr, const v8i32* qf, const float init, int r32, int hi) {
; #pragma unroll
;   for (int r = 0; r < 16; ++r) { p0[r] = init; p1[r] = init; }
; #pragma unroll
;   for (int s = 0; s < 2; ++s) { const int c0 = s * 4 + hi * 2;
;     const v8i32 a0 = cat8(*reinterpret_cast<const v4i32*>(Kn + KN8SW(r32, c0)), *reinterpret_cast<const v4i32*>(Kn + KN8SW(r32, c0 + 1)));
;     const v8i32 a1 = cat8(*reinterpret_cast<const v4i32*>(Kn + 4096 + KN8SW(r32, c0)), *reinterpret_cast<const v4i32*>(Kn + 4096 + KN8SW(r32, c0 + 1)));
;     p0 = __builtin_amdgcn_mfma_scale_f32_32x32x64_f8f6f4(a0, qf[s], p0, 0, 0, 0, 127, 0, 124);
;     p1 = __builtin_amdgcn_mfma_scale_f32_32x32x64_f8f6f4(a1, qf[s], p1, 0, 0, 0, 127, 0, 124); }
;   { const int c0 = hi * 2;
.Lmla_h5_cont:
	s_add_i32 s30, s30, 1
	s_cmpk_lt_u32 s30, 42
	s_cbranch_scc1 .LBB0_1321
	global_load_dwordx4 v[158:161], v176, s[18:19]
	global_load_dwordx4 v[162:165], v178, s[16:17]
	global_load_dwordx4 v[154:157], v[180:181], off
	ds_read_b128 v[114:117], v215 offset:24576
	ds_read_b128 v[118:121], v216 offset:24576
	ds_read_b128 v[222:225], v215 offset:28672
	ds_read_b128 v[226:229], v216 offset:28672
	v_exp_f32_e32 v0, v82
	v_exp_f32_e32 v177, v83
	v_exp_f32_e32 v179, v84
	v_exp_f32_e32 v254, v85
	v_add_f32_e32 v219, v0, v177
	v_cvt_pk_fp8_f32 v246, v0, v177
	v_add_f32_e32 v219, v179, v219
	v_add_f32_e32 v219, v254, v219
	v_cvt_pk_fp8_f32 v246, v179, v254 op_sel:[0,0,1]
	s_waitcnt lgkmcnt(2)
	v_mfma_scale_f32_32x32x64_f8f6f4 v[114:129], v[114:121], v[146:153], v[230:245], v194, v193 op_sel_hi:[0,0,0]
	v_exp_f32_e32 v0, v86
	v_exp_f32_e32 v177, v87
	v_exp_f32_e32 v179, v88
	v_exp_f32_e32 v254, v89
	v_add_f32_e32 v219, v0, v219
	v_add_f32_e32 v219, v177, v219
	v_cvt_pk_fp8_f32 v247, v0, v177
	v_add_f32_e32 v219, v179, v219
	v_add_f32_e32 v219, v254, v219
	v_cvt_pk_fp8_f32 v247, v179, v254 op_sel:[0,0,1]
	ds_read_b128 v[82:85], v213 offset:24576
	ds_read_b128 v[86:89], v214 offset:24576
	s_waitcnt lgkmcnt(2)
	v_mfma_scale_f32_32x32x64_f8f6f4 v[98:113], v[222:229], v[146:153], v[230:245], v194, v193 op_sel_hi:[0,0,0]
	ds_read_b128 v[222:225], v213 offset:28672
	ds_read_b128 v[226:229], v214 offset:28672
	v_exp_f32_e32 v0, v90
	v_exp_f32_e32 v177, v91
	v_exp_f32_e32 v179, v92
	v_exp_f32_e32 v254, v93
	v_add_f32_e32 v219, v0, v219
	v_add_f32_e32 v219, v177, v219
	v_cvt_pk_fp8_f32 v248, v0, v177
	v_add_f32_e32 v219, v179, v219
	v_add_f32_e32 v219, v254, v219
	v_cvt_pk_fp8_f32 v248, v179, v254 op_sel:[0,0,1]
	v_exp_f32_e32 v0, v94
	v_exp_f32_e32 v177, v95
	v_exp_f32_e32 v179, v96
	v_exp_f32_e32 v254, v97
	v_add_f32_e32 v219, v0, v219
	v_add_f32_e32 v219, v177, v219
	v_cvt_pk_fp8_f32 v249, v0, v177
	v_add_f32_e32 v219, v179, v219
	v_add_f32_e32 v219, v254, v219
	v_cvt_pk_fp8_f32 v249, v179, v254 op_sel:[0,0,1]
	ds_read_b128 v[90:93], v185 offset:36864
	ds_read_b128 v[94:97], v186 offset:36864
	s_waitcnt lgkmcnt(4)
	v_mfma_scale_f32_32x32x64_f8f6f4 v[114:129], v[82:89], v[138:145], v[114:129], v194, v193 op_sel_hi:[0,0,0]
	v_exp_f32_e32 v0, v66
	v_exp_f32_e32 v177, v67
	v_exp_f32_e32 v179, v68
	v_exp_f32_e32 v254, v69
	v_add_f32_e32 v219, v0, v219
	v_add_f32_e32 v219, v177, v219
	v_cvt_pk_fp8_f32 v250, v0, v177
	v_add_f32_e32 v219, v179, v219
	v_add_f32_e32 v219, v254, v219
	v_cvt_pk_fp8_f32 v250, v179, v254 op_sel:[0,0,1]
	s_waitcnt lgkmcnt(2)
	v_mfma_scale_f32_32x32x64_f8f6f4 v[98:113], v[222:229], v[138:145], v[98:113], v194, v193 op_sel_hi:[0,0,0]
	ds_read_b128 v[222:225], v185 offset:38912
	ds_read_b128 v[226:229], v186 offset:38912
	v_exp_f32_e32 v0, v70
	v_exp_f32_e32 v177, v71
	v_exp_f32_e32 v179, v72
	v_exp_f32_e32 v254, v73
	v_add_f32_e32 v219, v0, v219
	v_add_f32_e32 v219, v177, v219
	v_cvt_pk_fp8_f32 v251, v0, v177
	v_add_f32_e32 v219, v179, v219
	v_add_f32_e32 v219, v254, v219
	v_cvt_pk_fp8_f32 v251, v179, v254 op_sel:[0,0,1]
	v_exp_f32_e32 v0, v74
	v_exp_f32_e32 v177, v75
	v_exp_f32_e32 v179, v76
	v_exp_f32_e32 v254, v77
	v_add_f32_e32 v219, v0, v219
	v_add_f32_e32 v219, v177, v219
	v_cvt_pk_fp8_f32 v252, v0, v177
	v_add_f32_e32 v219, v179, v219
	v_add_f32_e32 v219, v254, v219
	v_cvt_pk_fp8_f32 v252, v179, v254 op_sel:[0,0,1]
	s_waitcnt lgkmcnt(2)
	v_mfma_scale_f32_32x32x64_f8f6f4 v[114:129], v[90:97], v[130:137], v[114:129], v194, v193 op_sel_hi:[0,0,0]
	v_exp_f32_e32 v0, v78
	v_exp_f32_e32 v177, v79
	v_exp_f32_e32 v179, v80
	v_exp_f32_e32 v254, v81
	v_add_f32_e32 v219, v0, v219
	v_add_f32_e32 v219, v177, v219
	v_cvt_pk_fp8_f32 v253, v0, v177
	v_add_f32_e32 v219, v179, v219
	v_add_f32_e32 v219, v254, v219
	v_cvt_pk_fp8_f32 v253, v179, v254 op_sel:[0,0,1]
	ds_read_b128 v[90:93], v185 offset:0
	ds_read_b128 v[94:97], v186 offset:0
	ds_read_b128 v[82:85], v185 offset:2048
	ds_read_b128 v[86:89], v186 offset:2048
	ds_read_b128 v[74:77], v185 offset:4096
	ds_read_b128 v[78:81], v186 offset:4096
	ds_read_b128 v[66:69], v185 offset:6144
	ds_read_b128 v[70:73], v186 offset:6144
	s_waitcnt lgkmcnt(8)
	v_mfma_scale_f32_32x32x64_f8f6f4 v[98:113], v[222:229], v[130:137], v[98:113], v194, v193 op_sel_hi:[0,0,0]
	v_mov_b32_e32 v0, v219
	s_nop 1
	v_permlane32_swap_b32_e32 v219, v0
	v_add_f32_e32 v219, v219, v0
	v_fma_f32 v209, v209, v218, v219
	v_add_u32_e32 v176, 0x2000, v176
	v_add_u32_e32 v178, 0x20000, v178
	s_mov_b64 s[20:21], 0x1000
	v_lshl_add_u64 v[180:181], v[180:181], 0, s[20:21]
	v_max_f32_e32 v177, v114, v115
	v_max3_f32 v177, v177, v116, v117
	v_max3_f32 v177, v177, v118, v119
	v_max3_f32 v177, v177, v120, v121
	v_max3_f32 v177, v177, v122, v123
	v_max3_f32 v177, v177, v124, v125
	v_max3_f32 v177, v177, v126, v127
	v_max3_f32 v177, v177, v128, v129
	s_waitcnt lgkmcnt(6)
	v_mfma_scale_f32_32x32x64_f8f6f4 v[50:65], v[246:253], v[90:97], v[50:65], v194, v194 op_sel_hi:[0,0,0]
	v_max_f32_e32 v0, v98, v99
	v_max3_f32 v0, v0, v100, v101
	v_max3_f32 v0, v0, v102, v103
	s_waitcnt lgkmcnt(4)
	v_mfma_scale_f32_32x32x64_f8f6f4 v[34:49], v[246:253], v[82:89], v[34:49], v194, v194 op_sel_hi:[0,0,0]
	v_max3_f32 v0, v0, v104, v105
	v_max3_f32 v0, v0, v106, v107
	v_max3_f32 v0, v0, v108, v109
	s_waitcnt lgkmcnt(2)
	v_mfma_scale_f32_32x32x64_f8f6f4 v[18:33], v[246:253], v[74:81], v[18:33], v194, v194 op_sel_hi:[0,0,0]
	v_max3_f32 v0, v0, v110, v111
	v_max3_f32 v0, v0, v112, v113
	v_max_f32_e32 v177, v177, v0
	v_mov_b32_e32 v0, v177
	v_mov_b32_e32 v221, 1.0
	s_waitcnt vmcnt(0)
	ds_write_b128 v210, v[158:161] offset:43008
	ds_write_b128 v211, v[162:165] offset:51200
	ds_write_b128 v212, v[154:157] offset:59392
	s_waitcnt lgkmcnt(3)
	v_mfma_scale_f32_32x32x64_f8f6f4 v[2:17], v[246:253], v[66:73], v[2:17], v194, v194 op_sel_hi:[0,0,0]
	s_waitcnt lgkmcnt(0)
	s_barrier
	v_permlane32_swap_b32_e32 v177, v0
	v_max_f32_e32 v177, v177, v0
	v_cmp_ge_f32_e32 vcc, s90, v177
	s_cmp_eq_u64 vcc, exec
	s_cbranch_scc0 .Lmla_p0_newmax

; __device__ __forceinline__ void finishSM9(f32x16& p0, f32x16& p1, float alpha, float& l_reg, v8i32& p8) {
; #pragma unroll
;   for (int r = 0; r < 16; ++r) { p0[r] = __builtin_amdgcn_exp2f(p0[r]); p1[r] = __builtin_amdgcn_exp2f(p1[r]); }
;   float ps = 0;
; #pragma unroll
;   for (int r = 0; r < 16; ++r) ps += p0[r];
; #pragma unroll
;   for (int r = 0; r < 16; ++r) ps += p1[r];
;   { auto rr = __builtin_amdgcn_permlane32_swap(__float_as_uint(ps), __float_as_uint(ps), false, false);
;     ps = __uint_as_float(rr[0]) + __uint_as_float(rr[1]); }
;   l_reg = l_reg * alpha + ps;
; #pragma unroll
;   for (int g = 0; g < 4; ++g) {
;     int w = __builtin_amdgcn_cvt_pk_fp8_f32(p0[4 * g], p0[4 * g + 1], 0, false); p8[g] = __builtin_amdgcn_cvt_pk_fp8_f32(p0[4 * g + 2], p0[4 * g + 3], w, true);
;     int u = __builtin_amdgcn_cvt_pk_fp8_f32(p1[4 * g], p1[4 * g + 1], 0, false); p8[4 + g] = __builtin_amdgcn_cvt_pk_fp8_f32(p1[4 * g + 2], p1[4 * g + 3], u, true); }
; }
; __device__ __forceinline__ void pv8(f32x16* o, const char* Vt, const v8i32 p8, int r32, int hi) {
;   const int sw = (r32 >> 2) & 3, a0 = r32 * 64 + (((hi * 2) ^ sw) << 4), a1 = r32 * 64 + (((hi * 2 + 1) ^ sw) << 4);
; #pragma unroll
;   for (int d0 = 0; d0 < 4; ++d0) {
;     const v8i32 vf = cat8(*reinterpret_cast<const v4i32*>(Vt + d0 * 2048 + a0), *reinterpret_cast<const v4i32*>(Vt + d0 * 2048 + a1));
;     o[d0] = __builtin_amdgcn_mfma_scale_f32_32x32x64_f8f6f4(p8, vf, o[d0], 0, 0, 0, 127, 0, 127); }
; }
; __device__ __forceinline__ void qkt9(f32x16& p0, f32x16& p1, const char* Kn, const char* Kr, const v8i32* qf, const float init, int r32, int hi) {
; #pragma unroll
;   for (int r = 0; r < 16; ++r) { p0[r] = init; p1[r] = init; }
; #pragma unroll
;   for (int s = 0; s < 2; ++s) { const int c0 = s * 4 + hi * 2;
;     const v8i32 a0 = cat8(*reinterpret_cast<const v4i32*>(Kn + KN8SW(r32, c0)), *reinterpret_cast<const v4i32*>(Kn + KN8SW(r32, c0 + 1)));
;     const v8i32 a1 = cat8(*reinterpret_cast<const v4i32*>(Kn + 4096 + KN8SW(r32, c0)), *reinterpret_cast<const v4i32*>(Kn + 4096 + KN8SW(r32, c0 + 1)));
;     p0 = __builtin_amdgcn_mfma_scale_f32_32x32x64_f8f6f4(a0, qf[s], p0, 0, 0, 0, 127, 0, 124);
;     p1 = __builtin_amdgcn_mfma_scale_f32_32x32x64_f8f6f4(a1, qf[s], p1, 0, 0, 0, 127, 0, 124); }
;   { const int c0 = hi * 2;
.Lmla_stag_loop:
	ds_read_b128 v[114:117], v215 offset:24576
	ds_read_b128 v[118:121], v216 offset:24576
	ds_read_b128 v[222:225], v215 offset:28672
	ds_read_b128 v[226:229], v216 offset:28672
	v_exp_f32_e32 v0, v82
	v_exp_f32_e32 v177, v83
	v_exp_f32_e32 v179, v84
	v_exp_f32_e32 v254, v85
	v_add_f32_e32 v219, v0, v177
	v_cvt_pk_fp8_f32 v246, v0, v177
	v_add_f32_e32 v219, v179, v219
	v_add_f32_e32 v219, v254, v219
	v_cvt_pk_fp8_f32 v246, v179, v254 op_sel:[0,0,1]
	s_waitcnt lgkmcnt(2)
	v_mfma_scale_f32_32x32x64_f8f6f4 v[114:129], v[114:121], v[146:153], v[230:245], v194, v193 op_sel_hi:[0,0,0]
	v_exp_f32_e32 v0, v86
	v_exp_f32_e32 v177, v87
	v_exp_f32_e32 v179, v88
	v_exp_f32_e32 v254, v89
	v_add_f32_e32 v219, v0, v219
	v_add_f32_e32 v219, v177, v219
	v_cvt_pk_fp8_f32 v247, v0, v177
	v_add_f32_e32 v219, v179, v219
	v_add_f32_e32 v219, v254, v219
	v_cvt_pk_fp8_f32 v247, v179, v254 op_sel:[0,0,1]
	ds_read_b128 v[82:85], v213 offset:24576
	ds_read_b128 v[86:89], v214 offset:24576
	s_waitcnt lgkmcnt(2)
	v_mfma_scale_f32_32x32x64_f8f6f4 v[98:113], v[222:229], v[146:153], v[230:245], v194, v193 op_sel_hi:[0,0,0]
	ds_read_b128 v[222:225], v213 offset:28672
	ds_read_b128 v[226:229], v214 offset:28672
	v_exp_f32_e32 v0, v90
	v_exp_f32_e32 v177, v91
	v_exp_f32_e32 v179, v92
	v_exp_f32_e32 v254, v93
	v_add_f32_e32 v219, v0, v219
	v_add_f32_e32 v219, v177, v219
	v_cvt_pk_fp8_f32 v248, v0, v177
	v_add_f32_e32 v219, v179, v219
	v_add_f32_e32 v219, v254, v219
	v_cvt_pk_fp8_f32 v248, v179, v254 op_sel:[0,0,1]
	v_exp_f32_e32 v0, v94
	v_exp_f32_e32 v177, v95
	v_exp_f32_e32 v179, v96
	v_exp_f32_e32 v254, v97
	v_add_f32_e32 v219, v0, v219
	v_add_f32_e32 v219, v177, v219
	v_cvt_pk_fp8_f32 v249, v0, v177
	v_add_f32_e32 v219, v179, v219
	v_add_f32_e32 v219, v254, v219
	v_cvt_pk_fp8_f32 v249, v179, v254 op_sel:[0,0,1]
	ds_read_b128 v[90:93], v185 offset:36864
	ds_read_b128 v[94:97], v186 offset:36864
	s_waitcnt lgkmcnt(4)
	v_mfma_scale_f32_32x32x64_f8f6f4 v[114:129], v[82:89], v[138:145], v[114:129], v194, v193 op_sel_hi:[0,0,0]
	v_exp_f32_e32 v0, v66
	v_exp_f32_e32 v177, v67
	v_exp_f32_e32 v179, v68
	v_exp_f32_e32 v254, v69
	v_add_f32_e32 v219, v0, v219
	v_add_f32_e32 v219, v177, v219
	v_cvt_pk_fp8_f32 v250, v0, v177
	v_add_f32_e32 v219, v179, v219
	v_add_f32_e32 v219, v254, v219
	v_cvt_pk_fp8_f32 v250, v179, v254 op_sel:[0,0,1]
	s_waitcnt lgkmcnt(2)
	v_mfma_scale_f32_32x32x64_f8f6f4 v[98:113], v[222:229], v[138:145], v[98:113], v194, v193 op_sel_hi:[0,0,0]
	ds_read_b128 v[222:225], v185 offset:38912
	ds_read_b128 v[226:229], v186 offset:38912
	v_exp_f32_e32 v0, v70
	v_exp_f32_e32 v177, v71
	v_exp_f32_e32 v179, v72
	v_exp_f32_e32 v254, v73
	v_add_f32_e32 v219, v0, v219
	v_add_f32_e32 v219, v177, v219
	v_cvt_pk_fp8_f32 v251, v0, v177
	v_add_f32_e32 v219, v179, v219
	v_add_f32_e32 v219, v254, v219
	v_cvt_pk_fp8_f32 v251, v179, v254 op_sel:[0,0,1]
	v_exp_f32_e32 v0, v74
	v_exp_f32_e32 v177, v75
	v_exp_f32_e32 v179, v76
	v_exp_f32_e32 v254, v77
	v_add_f32_e32 v219, v0, v219
	v_add_f32_e32 v219, v177, v219
	v_cvt_pk_fp8_f32 v252, v0, v177
	v_add_f32_e32 v219, v179, v219
	v_add_f32_e32 v219, v254, v219
	v_cvt_pk_fp8_f32 v252, v179, v254 op_sel:[0,0,1]
	s_waitcnt lgkmcnt(2)
	v_mfma_scale_f32_32x32x64_f8f6f4 v[114:129], v[90:97], v[130:137], v[114:129], v194, v193 op_sel_hi:[0,0,0]
	v_exp_f32_e32 v0, v78
	v_exp_f32_e32 v177, v79
	v_exp_f32_e32 v179, v80
	v_exp_f32_e32 v254, v81
	v_add_f32_e32 v219, v0, v219
	v_add_f32_e32 v219, v177, v219
	v_cvt_pk_fp8_f32 v253, v0, v177
	v_add_f32_e32 v219, v179, v219
	v_add_f32_e32 v219, v254, v219
	v_cvt_pk_fp8_f32 v253, v179, v254 op_sel:[0,0,1]
	ds_read_b128 v[90:93], v185 offset:0
	ds_read_b128 v[94:97], v186 offset:0
	ds_read_b128 v[82:85], v185 offset:2048
	ds_read_b128 v[86:89], v186 offset:2048
	ds_read_b128 v[74:77], v185 offset:4096
	ds_read_b128 v[78:81], v186 offset:4096
	ds_read_b128 v[66:69], v185 offset:6144
	ds_read_b128 v[70:73], v186 offset:6144
	s_waitcnt lgkmcnt(8)
	v_mfma_scale_f32_32x32x64_f8f6f4 v[98:113], v[222:229], v[130:137], v[98:113], v194, v193 op_sel_hi:[0,0,0]
	v_mov_b32_e32 v0, v219
	s_nop 1
	v_permlane32_swap_b32_e32 v219, v0
	v_add_f32_e32 v219, v219, v0
	v_fma_f32 v209, v209, v218, v219
	v_max_f32_e32 v177, v114, v115
	v_max3_f32 v177, v177, v116, v117
	v_max3_f32 v177, v177, v118, v119
	v_max3_f32 v177, v177, v120, v121
	v_max3_f32 v177, v177, v122, v123
	v_max3_f32 v177, v177, v124, v125
	v_max3_f32 v177, v177, v126, v127
	v_max3_f32 v177, v177, v128, v129
	s_waitcnt lgkmcnt(6)
	v_mfma_scale_f32_32x32x64_f8f6f4 v[50:65], v[246:253], v[90:97], v[50:65], v194, v194 op_sel_hi:[0,0,0]
	v_max_f32_e32 v0, v98, v99
	v_max3_f32 v0, v0, v100, v101
	v_max3_f32 v0, v0, v102, v103
	s_waitcnt vmcnt(0)
	ds_write_b128 v210, v[158:161] offset:43008
	ds_write_b128 v211, v[162:165] offset:51200
	s_waitcnt lgkmcnt(6)
	v_mfma_scale_f32_32x32x64_f8f6f4 v[34:49], v[246:253], v[82:89], v[34:49], v194, v194 op_sel_hi:[0,0,0]
	s_waitcnt lgkmcnt(0)
	s_barrier
	global_load_dwordx4 v[158:161], v176, s[18:19]
	global_load_dwordx4 v[162:165], v178, s[16:17]
	v_add_u32_e32 v176, 0x2000, v176
	v_add_u32_e32 v178, 0x20000, v178
	v_max3_f32 v0, v0, v104, v105
	v_max3_f32 v0, v0, v106, v107
	v_max3_f32 v0, v0, v108, v109
	s_waitcnt lgkmcnt(2)
	v_mfma_scale_f32_32x32x64_f8f6f4 v[18:33], v[246:253], v[74:81], v[18:33], v194, v194 op_sel_hi:[0,0,0]
	v_max3_f32 v0, v0, v110, v111
	v_max3_f32 v0, v0, v112, v113
	v_max_f32_e32 v177, v177, v0
	v_mov_b32_e32 v0, v177
	v_mov_b32_e32 v221, 1.0
	s_waitcnt lgkmcnt(0)
	v_mfma_scale_f32_32x32x64_f8f6f4 v[2:17], v[246:253], v[66:73], v[2:17], v194, v194 op_sel_hi:[0,0,0]
	s_nop 0
	v_permlane32_swap_b32_e32 v177, v0
	v_max_f32_e32 v177, v177, v0
	v_cmp_ge_f32_e32 vcc, s90, v177
	s_cmp_eq_u64 vcc, exec
	s_cbranch_scc0 .Lmla_s0_newmax
; __device__ __forceinline__ void finishSM9(f32x16& p0, f32x16& p1, float alpha, float& l_reg, v8i32& p8) {
; #pragma unroll
;   for (int r = 0; r < 16; ++r) { p0[r] = __builtin_amdgcn_exp2f(p0[r]); p1[r] = __builtin_amdgcn_exp2f(p1[r]); }
;   float ps = 0;
; #pragma unroll
;   for (int r = 0; r < 16; ++r) ps += p0[r];
; #pragma unroll
;   for (int r = 0; r < 16; ++r) ps += p1[r];
;   { auto rr = __builtin_amdgcn_permlane32_swap(__float_as_uint(ps), __float_as_uint(ps), false, false);
;     ps = __uint_as_float(rr[0]) + __uint_as_float(rr[1]); }
;   l_reg = l_reg * alpha + ps;
; #pragma unroll
;   for (int g = 0; g < 4; ++g) {
;     int w = __builtin_amdgcn_cvt_pk_fp8_f32(p0[4 * g], p0[4 * g + 1], 0, false); p8[g] = __builtin_amdgcn_cvt_pk_fp8_f32(p0[4 * g + 2], p0[4 * g + 3], w, true);
;     int u = __builtin_amdgcn_cvt_pk_fp8_f32(p1[4 * g], p1[4 * g + 1], 0, false); p8[4 + g] = __builtin_amdgcn_cvt_pk_fp8_f32(p1[4 * g + 2], p1[4 * g + 3], u, true); }
; }
; __device__ __forceinline__ void pv8(f32x16* o, const char* Vt, const v8i32 p8, int r32, int hi) {
;   const int sw = (r32 >> 2) & 3, a0 = r32 * 64 + (((hi * 2) ^ sw) << 4), a1 = r32 * 64 + (((hi * 2 + 1) ^ sw) << 4);
; #pragma unroll
;   for (int d0 = 0; d0 < 4; ++d0) {
;     const v8i32 vf = cat8(*reinterpret_cast<const v4i32*>(Vt + d0 * 2048 + a0), *reinterpret_cast<const v4i32*>(Vt + d0 * 2048 + a1));
;     o[d0] = __builtin_amdgcn_mfma_scale_f32_32x32x64_f8f6f4(p8, vf, o[d0], 0, 0, 0, 127, 0, 127); }
; }
; __device__ __forceinline__ void qkt9(f32x16& p0, f32x16& p1, const char* Kn, const char* Kr, const v8i32* qf, const float init, int r32, int hi) {
; #pragma unroll
;   for (int r = 0; r < 16; ++r) { p0[r] = init; p1[r] = init; }
; #pragma unroll
;   for (int s = 0; s < 2; ++s) { const int c0 = s * 4 + hi * 2;
;     const v8i32 a0 = cat8(*reinterpret_cast<const v4i32*>(Kn + KN8SW(r32, c0)), *reinterpret_cast<const v4i32*>(Kn + KN8SW(r32, c0 + 1)));
;     const v8i32 a1 = cat8(*reinterpret_cast<const v4i32*>(Kn + 4096 + KN8SW(r32, c0)), *reinterpret_cast<const v4i32*>(Kn + 4096 + KN8SW(r32, c0 + 1)));
;     p0 = __builtin_amdgcn_mfma_scale_f32_32x32x64_f8f6f4(a0, qf[s], p0, 0, 0, 0, 127, 0, 124);
;     p1 = __builtin_amdgcn_mfma_scale_f32_32x32x64_f8f6f4(a1, qf[s], p1, 0, 0, 0, 127, 0, 124); }
;   { const int c0 = hi * 2;
.Lmla_s0_cont:
	ds_read_b128 v[82:85], v215 offset:51200
	ds_read_b128 v[86:89], v216 offset:51200
	ds_read_b128 v[222:225], v215 offset:55296
	ds_read_b128 v[226:229], v216 offset:55296
	v_exp_f32_e32 v0, v114
	v_exp_f32_e32 v177, v115
	v_exp_f32_e32 v179, v116
	v_exp_f32_e32 v254, v117
	v_add_f32_e32 v219, v0, v177
	v_cvt_pk_fp8_f32 v246, v0, v177
	v_add_f32_e32 v219, v179, v219
	v_add_f32_e32 v219, v254, v219
	v_cvt_pk_fp8_f32 v246, v179, v254 op_sel:[0,0,1]
	s_waitcnt lgkmcnt(2)
	v_mfma_scale_f32_32x32x64_f8f6f4 v[82:97], v[82:89], v[146:153], v[230:245], v194, v193 op_sel_hi:[0,0,0]
	v_exp_f32_e32 v0, v118
	v_exp_f32_e32 v177, v119
	v_exp_f32_e32 v179, v120
	v_exp_f32_e32 v254, v121
	v_add_f32_e32 v219, v0, v219
	v_add_f32_e32 v219, v177, v219
	v_cvt_pk_fp8_f32 v247, v0, v177
	v_add_f32_e32 v219, v179, v219
	v_add_f32_e32 v219, v254, v219
	v_cvt_pk_fp8_f32 v247, v179, v254 op_sel:[0,0,1]
	ds_read_b128 v[114:117], v213 offset:51200
	ds_read_b128 v[118:121], v214 offset:51200
	s_waitcnt lgkmcnt(2)
	v_mfma_scale_f32_32x32x64_f8f6f4 v[66:81], v[222:229], v[146:153], v[230:245], v194, v193 op_sel_hi:[0,0,0]
	ds_read_b128 v[222:225], v213 offset:55296
	ds_read_b128 v[226:229], v214 offset:55296
	v_exp_f32_e32 v0, v122
	v_exp_f32_e32 v177, v123
	v_exp_f32_e32 v179, v124
	v_exp_f32_e32 v254, v125
	v_add_f32_e32 v219, v0, v219
	v_add_f32_e32 v219, v177, v219
	v_cvt_pk_fp8_f32 v248, v0, v177
	v_add_f32_e32 v219, v179, v219
	v_add_f32_e32 v219, v254, v219
	v_cvt_pk_fp8_f32 v248, v179, v254 op_sel:[0,0,1]
	v_exp_f32_e32 v0, v126
	v_exp_f32_e32 v177, v127
	v_exp_f32_e32 v179, v128
	v_exp_f32_e32 v254, v129
	v_add_f32_e32 v219, v0, v219
	v_add_f32_e32 v219, v177, v219
	v_cvt_pk_fp8_f32 v249, v0, v177
	v_add_f32_e32 v219, v179, v219
	v_add_f32_e32 v219, v254, v219
	v_cvt_pk_fp8_f32 v249, v179, v254 op_sel:[0,0,1]
	ds_read_b128 v[122:125], v185 offset:59392
	ds_read_b128 v[126:129], v186 offset:59392
	s_waitcnt lgkmcnt(4)
	v_mfma_scale_f32_32x32x64_f8f6f4 v[82:97], v[114:121], v[138:145], v[82:97], v194, v193 op_sel_hi:[0,0,0]
	v_exp_f32_e32 v0, v98
	v_exp_f32_e32 v177, v99
	v_exp_f32_e32 v179, v100
	v_exp_f32_e32 v254, v101
	v_add_f32_e32 v219, v0, v219
	v_add_f32_e32 v219, v177, v219
	v_cvt_pk_fp8_f32 v250, v0, v177
	v_add_f32_e32 v219, v179, v219
	v_add_f32_e32 v219, v254, v219
	v_cvt_pk_fp8_f32 v250, v179, v254 op_sel:[0,0,1]
	s_waitcnt lgkmcnt(2)
	v_mfma_scale_f32_32x32x64_f8f6f4 v[66:81], v[222:229], v[138:145], v[66:81], v194, v193 op_sel_hi:[0,0,0]
	ds_read_b128 v[222:225], v185 offset:61440
	ds_read_b128 v[226:229], v186 offset:61440
	v_exp_f32_e32 v0, v102
	v_exp_f32_e32 v177, v103
	v_exp_f32_e32 v179, v104
	v_exp_f32_e32 v254, v105
	v_add_f32_e32 v219, v0, v219
	v_add_f32_e32 v219, v177, v219
	v_cvt_pk_fp8_f32 v251, v0, v177
	v_add_f32_e32 v219, v179, v219
	v_add_f32_e32 v219, v254, v219
	v_cvt_pk_fp8_f32 v251, v179, v254 op_sel:[0,0,1]
	v_exp_f32_e32 v0, v106
	v_exp_f32_e32 v177, v107
	v_exp_f32_e32 v179, v108
	v_exp_f32_e32 v254, v109
	v_add_f32_e32 v219, v0, v219
	v_add_f32_e32 v219, v177, v219
	v_cvt_pk_fp8_f32 v252, v0, v177
	v_add_f32_e32 v219, v179, v219
	v_add_f32_e32 v219, v254, v219
	v_cvt_pk_fp8_f32 v252, v179, v254 op_sel:[0,0,1]
	s_waitcnt lgkmcnt(2)
	v_mfma_scale_f32_32x32x64_f8f6f4 v[82:97], v[122:129], v[130:137], v[82:97], v194, v193 op_sel_hi:[0,0,0]
	v_exp_f32_e32 v0, v110
	v_exp_f32_e32 v177, v111
	v_exp_f32_e32 v179, v112
	v_exp_f32_e32 v254, v113
	v_add_f32_e32 v219, v0, v219
	v_add_f32_e32 v219, v177, v219
	v_cvt_pk_fp8_f32 v253, v0, v177
	v_add_f32_e32 v219, v179, v219
	v_add_f32_e32 v219, v254, v219
	v_cvt_pk_fp8_f32 v253, v179, v254 op_sel:[0,0,1]
	ds_read_b128 v[122:125], v185 offset:8192
	ds_read_b128 v[126:129], v186 offset:8192
	ds_read_b128 v[114:117], v185 offset:10240
	ds_read_b128 v[118:121], v186 offset:10240
	ds_read_b128 v[106:109], v185 offset:12288
	ds_read_b128 v[110:113], v186 offset:12288
	ds_read_b128 v[98:101], v185 offset:14336
	ds_read_b128 v[102:105], v186 offset:14336
	s_waitcnt lgkmcnt(8)
	v_mfma_scale_f32_32x32x64_f8f6f4 v[66:81], v[222:229], v[130:137], v[66:81], v194, v193 op_sel_hi:[0,0,0]
	v_mov_b32_e32 v0, v219
	s_nop 1
	v_permlane32_swap_b32_e32 v219, v0
	v_add_f32_e32 v219, v219, v0
	v_fma_f32 v209, v209, v221, v219
	v_max_f32_e32 v177, v82, v83
	v_max3_f32 v177, v177, v84, v85
	v_max3_f32 v177, v177, v86, v87
	v_max3_f32 v177, v177, v88, v89
	v_max3_f32 v177, v177, v90, v91
	v_max3_f32 v177, v177, v92, v93
	v_max3_f32 v177, v177, v94, v95
	v_max3_f32 v177, v177, v96, v97
	s_waitcnt lgkmcnt(6)
	v_mfma_scale_f32_32x32x64_f8f6f4 v[50:65], v[246:253], v[122:129], v[50:65], v194, v194 op_sel_hi:[0,0,0]
	v_max_f32_e32 v0, v66, v67
	v_max3_f32 v0, v0, v68, v69
	v_max3_f32 v0, v0, v70, v71
	s_waitcnt vmcnt(0)
	ds_write_b128 v210, v[158:161]
	ds_write_b128 v211, v[162:165] offset:16384
	s_waitcnt lgkmcnt(6)
	v_mfma_scale_f32_32x32x64_f8f6f4 v[34:49], v[246:253], v[114:121], v[34:49], v194, v194 op_sel_hi:[0,0,0]
	s_waitcnt lgkmcnt(0)
	s_barrier
	global_load_dwordx4 v[158:161], v176, s[18:19]
	global_load_dwordx4 v[162:165], v178, s[16:17]
	v_add_u32_e32 v176, 0x2000, v176
	v_add_u32_e32 v178, 0x20000, v178
	v_max3_f32 v0, v0, v72, v73
	v_max3_f32 v0, v0, v74, v75
	v_max3_f32 v0, v0, v76, v77
	s_waitcnt lgkmcnt(2)
	v_mfma_scale_f32_32x32x64_f8f6f4 v[18:33], v[246:253], v[106:113], v[18:33], v194, v194 op_sel_hi:[0,0,0]
	v_max3_f32 v0, v0, v78, v79
	v_max3_f32 v0, v0, v80, v81
	v_max_f32_e32 v177, v177, v0
	v_mov_b32_e32 v0, v177
	v_mov_b32_e32 v218, 1.0
	s_waitcnt lgkmcnt(0)
	v_mfma_scale_f32_32x32x64_f8f6f4 v[2:17], v[246:253], v[98:105], v[2:17], v194, v194 op_sel_hi:[0,0,0]
	s_nop 0
	v_permlane32_swap_b32_e32 v177, v0
	v_max_f32_e32 v177, v177, v0
	v_cmp_ge_f32_e32 vcc, s90, v177
	s_cmp_eq_u64 vcc, exec
	s_cbranch_scc0 .Lmla_s1_newmax
; __device__ __forceinline__ void finishSM9(f32x16& p0, f32x16& p1, float alpha, float& l_reg, v8i32& p8) {
; #pragma unroll
;   for (int r = 0; r < 16; ++r) { p0[r] = __builtin_amdgcn_exp2f(p0[r]); p1[r] = __builtin_amdgcn_exp2f(p1[r]); }
;   float ps = 0;
; #pragma unroll
;   for (int r = 0; r < 16; ++r) ps += p0[r];
; #pragma unroll
;   for (int r = 0; r < 16; ++r) ps += p1[r];
;   { auto rr = __builtin_amdgcn_permlane32_swap(__float_as_uint(ps), __float_as_uint(ps), false, false);
;     ps = __uint_as_float(rr[0]) + __uint_as_float(rr[1]); }
;   l_reg = l_reg * alpha + ps;
; #pragma unroll
;   for (int g = 0; g < 4; ++g) {
;     int w = __builtin_amdgcn_cvt_pk_fp8_f32(p0[4 * g], p0[4 * g + 1], 0, false); p8[g] = __builtin_amdgcn_cvt_pk_fp8_f32(p0[4 * g + 2], p0[4 * g + 3], w, true);
;     int u = __builtin_amdgcn_cvt_pk_fp8_f32(p1[4 * g], p1[4 * g + 1], 0, false); p8[4 + g] = __builtin_amdgcn_cvt_pk_fp8_f32(p1[4 * g + 2], p1[4 * g + 3], u, true); }
; }
; __device__ __forceinline__ void pv8(f32x16* o, const char* Vt, const v8i32 p8, int r32, int hi) {
;   const int sw = (r32 >> 2) & 3, a0 = r32 * 64 + (((hi * 2) ^ sw) << 4), a1 = r32 * 64 + (((hi * 2 + 1) ^ sw) << 4);
; #pragma unroll
;   for (int d0 = 0; d0 < 4; ++d0) {
;     const v8i32 vf = cat8(*reinterpret_cast<const v4i32*>(Vt + d0 * 2048 + a0), *reinterpret_cast<const v4i32*>(Vt + d0 * 2048 + a1));
;     o[d0] = __builtin_amdgcn_mfma_scale_f32_32x32x64_f8f6f4(p8, vf, o[d0], 0, 0, 0, 127, 0, 127); }
; }
; __device__ __forceinline__ void qkt9(f32x16& p0, f32x16& p1, const char* Kn, const char* Kr, const v8i32* qf, const float init, int r32, int hi) {
; #pragma unroll
;   for (int r = 0; r < 16; ++r) { p0[r] = init; p1[r] = init; }
; #pragma unroll
;   for (int s = 0; s < 2; ++s) { const int c0 = s * 4 + hi * 2;
;     const v8i32 a0 = cat8(*reinterpret_cast<const v4i32*>(Kn + KN8SW(r32, c0)), *reinterpret_cast<const v4i32*>(Kn + KN8SW(r32, c0 + 1)));
;     const v8i32 a1 = cat8(*reinterpret_cast<const v4i32*>(Kn + 4096 + KN8SW(r32, c0)), *reinterpret_cast<const v4i32*>(Kn + 4096 + KN8SW(r32, c0 + 1)));
;     p0 = __builtin_amdgcn_mfma_scale_f32_32x32x64_f8f6f4(a0, qf[s], p0, 0, 0, 0, 127, 0, 124);
;     p1 = __builtin_amdgcn_mfma_scale_f32_32x32x64_f8f6f4(a1, qf[s], p1, 0, 0, 0, 127, 0, 124); }
;   { const int c0 = hi * 2;
.Lmla_s1_cont:
	ds_read_b128 v[114:117], v215 offset:16384
	ds_read_b128 v[118:121], v216 offset:16384
	ds_read_b128 v[222:225], v215 offset:20480
	ds_read_b128 v[226:229], v216 offset:20480
	v_exp_f32_e32 v0, v82
	v_exp_f32_e32 v177, v83
	v_exp_f32_e32 v179, v84
	v_exp_f32_e32 v254, v85
	v_add_f32_e32 v219, v0, v177
	v_cvt_pk_fp8_f32 v246, v0, v177
	v_add_f32_e32 v219, v179, v219
	v_add_f32_e32 v219, v254, v219
	v_cvt_pk_fp8_f32 v246, v179, v254 op_sel:[0,0,1]
	s_waitcnt lgkmcnt(2)
	v_mfma_scale_f32_32x32x64_f8f6f4 v[114:129], v[114:121], v[146:153], v[230:245], v194, v193 op_sel_hi:[0,0,0]
	v_exp_f32_e32 v0, v86
	v_exp_f32_e32 v177, v87
	v_exp_f32_e32 v179, v88
	v_exp_f32_e32 v254, v89
	v_add_f32_e32 v219, v0, v219
	v_add_f32_e32 v219, v177, v219
	v_cvt_pk_fp8_f32 v247, v0, v177
	v_add_f32_e32 v219, v179, v219
	v_add_f32_e32 v219, v254, v219
	v_cvt_pk_fp8_f32 v247, v179, v254 op_sel:[0,0,1]
	ds_read_b128 v[82:85], v213 offset:16384
	ds_read_b128 v[86:89], v214 offset:16384
	s_waitcnt lgkmcnt(2)
	v_mfma_scale_f32_32x32x64_f8f6f4 v[98:113], v[222:229], v[146:153], v[230:245], v194, v193 op_sel_hi:[0,0,0]
	ds_read_b128 v[222:225], v213 offset:20480
	ds_read_b128 v[226:229], v214 offset:20480
	v_exp_f32_e32 v0, v90
	v_exp_f32_e32 v177, v91
	v_exp_f32_e32 v179, v92
	v_exp_f32_e32 v254, v93
	v_add_f32_e32 v219, v0, v219
	v_add_f32_e32 v219, v177, v219
	v_cvt_pk_fp8_f32 v248, v0, v177
	v_add_f32_e32 v219, v179, v219
	v_add_f32_e32 v219, v254, v219
	v_cvt_pk_fp8_f32 v248, v179, v254 op_sel:[0,0,1]
	v_exp_f32_e32 v0, v94
	v_exp_f32_e32 v177, v95
	v_exp_f32_e32 v179, v96
	v_exp_f32_e32 v254, v97
	v_add_f32_e32 v219, v0, v219
	v_add_f32_e32 v219, v177, v219
	v_cvt_pk_fp8_f32 v249, v0, v177
	v_add_f32_e32 v219, v179, v219
	v_add_f32_e32 v219, v254, v219
	v_cvt_pk_fp8_f32 v249, v179, v254 op_sel:[0,0,1]
	ds_read_b128 v[90:93], v185 offset:32768
	ds_read_b128 v[94:97], v186 offset:32768
	s_waitcnt lgkmcnt(4)
	v_mfma_scale_f32_32x32x64_f8f6f4 v[114:129], v[82:89], v[138:145], v[114:129], v194, v193 op_sel_hi:[0,0,0]
	v_exp_f32_e32 v0, v66
	v_exp_f32_e32 v177, v67
	v_exp_f32_e32 v179, v68
	v_exp_f32_e32 v254, v69
	v_add_f32_e32 v219, v0, v219
	v_add_f32_e32 v219, v177, v219
	v_cvt_pk_fp8_f32 v250, v0, v177
	v_add_f32_e32 v219, v179, v219
	v_add_f32_e32 v219, v254, v219
	v_cvt_pk_fp8_f32 v250, v179, v254 op_sel:[0,0,1]
	s_waitcnt lgkmcnt(2)
	v_mfma_scale_f32_32x32x64_f8f6f4 v[98:113], v[222:229], v[138:145], v[98:113], v194, v193 op_sel_hi:[0,0,0]
	ds_read_b128 v[222:225], v185 offset:34816
	ds_read_b128 v[226:229], v186 offset:34816
	v_exp_f32_e32 v0, v70
	v_exp_f32_e32 v177, v71
	v_exp_f32_e32 v179, v72
	v_exp_f32_e32 v254, v73
	v_add_f32_e32 v219, v0, v219
	v_add_f32_e32 v219, v177, v219
	v_cvt_pk_fp8_f32 v251, v0, v177
	v_add_f32_e32 v219, v179, v219
	v_add_f32_e32 v219, v254, v219
	v_cvt_pk_fp8_f32 v251, v179, v254 op_sel:[0,0,1]
	v_exp_f32_e32 v0, v74
	v_exp_f32_e32 v177, v75
	v_exp_f32_e32 v179, v76
	v_exp_f32_e32 v254, v77
	v_add_f32_e32 v219, v0, v219
	v_add_f32_e32 v219, v177, v219
	v_cvt_pk_fp8_f32 v252, v0, v177
	v_add_f32_e32 v219, v179, v219
	v_add_f32_e32 v219, v254, v219
	v_cvt_pk_fp8_f32 v252, v179, v254 op_sel:[0,0,1]
	s_waitcnt lgkmcnt(2)
	v_mfma_scale_f32_32x32x64_f8f6f4 v[114:129], v[90:97], v[130:137], v[114:129], v194, v193 op_sel_hi:[0,0,0]
	v_exp_f32_e32 v0, v78
	v_exp_f32_e32 v177, v79
	v_exp_f32_e32 v179, v80
	v_exp_f32_e32 v254, v81
	v_add_f32_e32 v219, v0, v219
	v_add_f32_e32 v219, v177, v219
	v_cvt_pk_fp8_f32 v253, v0, v177
	v_add_f32_e32 v219, v179, v219
	v_add_f32_e32 v219, v254, v219
	v_cvt_pk_fp8_f32 v253, v179, v254 op_sel:[0,0,1]
	ds_read_b128 v[90:93], v185 offset:43008
	ds_read_b128 v[94:97], v186 offset:43008
	ds_read_b128 v[82:85], v185 offset:45056
	ds_read_b128 v[86:89], v186 offset:45056
	ds_read_b128 v[74:77], v185 offset:47104
	ds_read_b128 v[78:81], v186 offset:47104
	ds_read_b128 v[66:69], v185 offset:49152
	ds_read_b128 v[70:73], v186 offset:49152
	s_waitcnt lgkmcnt(8)
	v_mfma_scale_f32_32x32x64_f8f6f4 v[98:113], v[222:229], v[130:137], v[98:113], v194, v193 op_sel_hi:[0,0,0]
	v_mov_b32_e32 v0, v219
	s_nop 1
	v_permlane32_swap_b32_e32 v219, v0
	v_add_f32_e32 v219, v219, v0
	v_fma_f32 v209, v209, v218, v219
	v_max_f32_e32 v177, v114, v115
	v_max3_f32 v177, v177, v116, v117
	v_max3_f32 v177, v177, v118, v119
	v_max3_f32 v177, v177, v120, v121
	v_max3_f32 v177, v177, v122, v123
	v_max3_f32 v177, v177, v124, v125
	v_max3_f32 v177, v177, v126, v127
	v_max3_f32 v177, v177, v128, v129
	s_waitcnt lgkmcnt(6)
	v_mfma_scale_f32_32x32x64_f8f6f4 v[50:65], v[246:253], v[90:97], v[50:65], v194, v194 op_sel_hi:[0,0,0]
	v_max_f32_e32 v0, v98, v99
	v_max3_f32 v0, v0, v100, v101
	v_max3_f32 v0, v0, v102, v103
	s_waitcnt vmcnt(0)
	ds_write_b128 v210, v[158:161] offset:8192
	ds_write_b128 v211, v[162:165] offset:24576
	s_waitcnt lgkmcnt(6)
	v_mfma_scale_f32_32x32x64_f8f6f4 v[34:49], v[246:253], v[82:89], v[34:49], v194, v194 op_sel_hi:[0,0,0]
	s_waitcnt lgkmcnt(0)
	s_barrier
	global_load_dwordx4 v[158:161], v176, s[18:19]
	global_load_dwordx4 v[162:165], v178, s[16:17]
	v_add_u32_e32 v176, 0x2000, v176
	v_add_u32_e32 v178, 0x20000, v178
	v_max3_f32 v0, v0, v104, v105
	v_max3_f32 v0, v0, v106, v107
	v_max3_f32 v0, v0, v108, v109
	s_waitcnt lgkmcnt(2)
	v_mfma_scale_f32_32x32x64_f8f6f4 v[18:33], v[246:253], v[74:81], v[18:33], v194, v194 op_sel_hi:[0,0,0]
	v_max3_f32 v0, v0, v110, v111
	v_max3_f32 v0, v0, v112, v113
	v_max_f32_e32 v177, v177, v0
	v_mov_b32_e32 v0, v177
	v_mov_b32_e32 v221, 1.0
	s_waitcnt lgkmcnt(0)
	v_mfma_scale_f32_32x32x64_f8f6f4 v[2:17], v[246:253], v[66:73], v[2:17], v194, v194 op_sel_hi:[0,0,0]
	s_nop 0
	v_permlane32_swap_b32_e32 v177, v0
	v_max_f32_e32 v177, v177, v0
	v_cmp_ge_f32_e32 vcc, s90, v177
	s_cmp_eq_u64 vcc, exec
	s_cbranch_scc0 .Lmla_s2_newmax
; __device__ __forceinline__ void finishSM9(f32x16& p0, f32x16& p1, float alpha, float& l_reg, v8i32& p8) {
; #pragma unroll
;   for (int r = 0; r < 16; ++r) { p0[r] = __builtin_amdgcn_exp2f(p0[r]); p1[r] = __builtin_amdgcn_exp2f(p1[r]); }
;   float ps = 0;
; #pragma unroll
;   for (int r = 0; r < 16; ++r) ps += p0[r];
; #pragma unroll
;   for (int r = 0; r < 16; ++r) ps += p1[r];
;   { auto rr = __builtin_amdgcn_permlane32_swap(__float_as_uint(ps), __float_as_uint(ps), false, false);
;     ps = __uint_as_float(rr[0]) + __uint_as_float(rr[1]); }
;   l_reg = l_reg * alpha + ps;
; #pragma unroll
;   for (int g = 0; g < 4; ++g) {
;     int w = __builtin_amdgcn_cvt_pk_fp8_f32(p0[4 * g], p0[4 * g + 1], 0, false); p8[g] = __builtin_amdgcn_cvt_pk_fp8_f32(p0[4 * g + 2], p0[4 * g + 3], w, true);
;     int u = __builtin_amdgcn_cvt_pk_fp8_f32(p1[4 * g], p1[4 * g + 1], 0, false); p8[4 + g] = __builtin_amdgcn_cvt_pk_fp8_f32(p1[4 * g + 2], p1[4 * g + 3], u, true); }
; }
; __device__ __forceinline__ void pv8(f32x16* o, const char* Vt, const v8i32 p8, int r32, int hi) {
;   const int sw = (r32 >> 2) & 3, a0 = r32 * 64 + (((hi * 2) ^ sw) << 4), a1 = r32 * 64 + (((hi * 2 + 1) ^ sw) << 4);
; #pragma unroll
;   for (int d0 = 0; d0 < 4; ++d0) {
;     const v8i32 vf = cat8(*reinterpret_cast<const v4i32*>(Vt + d0 * 2048 + a0), *reinterpret_cast<const v4i32*>(Vt + d0 * 2048 + a1));
;     o[d0] = __builtin_amdgcn_mfma_scale_f32_32x32x64_f8f6f4(p8, vf, o[d0], 0, 0, 0, 127, 0, 127); }
; }
; __device__ __forceinline__ void qkt9(f32x16& p0, f32x16& p1, const char* Kn, const char* Kr, const v8i32* qf, const float init, int r32, int hi) {
; #pragma unroll
;   for (int r = 0; r < 16; ++r) { p0[r] = init; p1[r] = init; }
; #pragma unroll
;   for (int s = 0; s < 2; ++s) { const int c0 = s * 4 + hi * 2;
;     const v8i32 a0 = cat8(*reinterpret_cast<const v4i32*>(Kn + KN8SW(r32, c0)), *reinterpret_cast<const v4i32*>(Kn + KN8SW(r32, c0 + 1)));
;     const v8i32 a1 = cat8(*reinterpret_cast<const v4i32*>(Kn + 4096 + KN8SW(r32, c0)), *reinterpret_cast<const v4i32*>(Kn + 4096 + KN8SW(r32, c0 + 1)));
;     p0 = __builtin_amdgcn_mfma_scale_f32_32x32x64_f8f6f4(a0, qf[s], p0, 0, 0, 0, 127, 0, 124);
;     p1 = __builtin_amdgcn_mfma_scale_f32_32x32x64_f8f6f4(a1, qf[s], p1, 0, 0, 0, 127, 0, 124); }
;   { const int c0 = hi * 2;
.Lmla_s2_cont:
	ds_read_b128 v[82:85], v215 offset:24576
	ds_read_b128 v[86:89], v216 offset:24576
	ds_read_b128 v[222:225], v215 offset:28672
	ds_read_b128 v[226:229], v216 offset:28672
	v_exp_f32_e32 v0, v114
	v_exp_f32_e32 v177, v115
	v_exp_f32_e32 v179, v116
	v_exp_f32_e32 v254, v117
	v_add_f32_e32 v219, v0, v177
	v_cvt_pk_fp8_f32 v246, v0, v177
	v_add_f32_e32 v219, v179, v219
	v_add_f32_e32 v219, v254, v219
	v_cvt_pk_fp8_f32 v246, v179, v254 op_sel:[0,0,1]
	s_waitcnt lgkmcnt(2)
	v_mfma_scale_f32_32x32x64_f8f6f4 v[82:97], v[82:89], v[146:153], v[230:245], v194, v193 op_sel_hi:[0,0,0]
	v_exp_f32_e32 v0, v118
	v_exp_f32_e32 v177, v119
	v_exp_f32_e32 v179, v120
	v_exp_f32_e32 v254, v121
	v_add_f32_e32 v219, v0, v219
	v_add_f32_e32 v219, v177, v219
	v_cvt_pk_fp8_f32 v247, v0, v177
	v_add_f32_e32 v219, v179, v219
	v_add_f32_e32 v219, v254, v219
	v_cvt_pk_fp8_f32 v247, v179, v254 op_sel:[0,0,1]
	ds_read_b128 v[114:117], v213 offset:24576
	ds_read_b128 v[118:121], v214 offset:24576
	s_waitcnt lgkmcnt(2)
	v_mfma_scale_f32_32x32x64_f8f6f4 v[66:81], v[222:229], v[146:153], v[230:245], v194, v193 op_sel_hi:[0,0,0]
	ds_read_b128 v[222:225], v213 offset:28672
	ds_read_b128 v[226:229], v214 offset:28672
	v_exp_f32_e32 v0, v122
	v_exp_f32_e32 v177, v123
	v_exp_f32_e32 v179, v124
	v_exp_f32_e32 v254, v125
	v_add_f32_e32 v219, v0, v219
	v_add_f32_e32 v219, v177, v219
	v_cvt_pk_fp8_f32 v248, v0, v177
	v_add_f32_e32 v219, v179, v219
	v_add_f32_e32 v219, v254, v219
	v_cvt_pk_fp8_f32 v248, v179, v254 op_sel:[0,0,1]
	v_exp_f32_e32 v0, v126
	v_exp_f32_e32 v177, v127
	v_exp_f32_e32 v179, v128
	v_exp_f32_e32 v254, v129
	v_add_f32_e32 v219, v0, v219
	v_add_f32_e32 v219, v177, v219
	v_cvt_pk_fp8_f32 v249, v0, v177
	v_add_f32_e32 v219, v179, v219
	v_add_f32_e32 v219, v254, v219
	v_cvt_pk_fp8_f32 v249, v179, v254 op_sel:[0,0,1]
	ds_read_b128 v[122:125], v185 offset:36864
	ds_read_b128 v[126:129], v186 offset:36864
	s_waitcnt lgkmcnt(4)
	v_mfma_scale_f32_32x32x64_f8f6f4 v[82:97], v[114:121], v[138:145], v[82:97], v194, v193 op_sel_hi:[0,0,0]
	v_exp_f32_e32 v0, v98
	v_exp_f32_e32 v177, v99
	v_exp_f32_e32 v179, v100
	v_exp_f32_e32 v254, v101
	v_add_f32_e32 v219, v0, v219
	v_add_f32_e32 v219, v177, v219
	v_cvt_pk_fp8_f32 v250, v0, v177
	v_add_f32_e32 v219, v179, v219
	v_add_f32_e32 v219, v254, v219
	v_cvt_pk_fp8_f32 v250, v179, v254 op_sel:[0,0,1]
	s_waitcnt lgkmcnt(2)
	v_mfma_scale_f32_32x32x64_f8f6f4 v[66:81], v[222:229], v[138:145], v[66:81], v194, v193 op_sel_hi:[0,0,0]
	ds_read_b128 v[222:225], v185 offset:38912
	ds_read_b128 v[226:229], v186 offset:38912
	v_exp_f32_e32 v0, v102
	v_exp_f32_e32 v177, v103
	v_exp_f32_e32 v179, v104
	v_exp_f32_e32 v254, v105
	v_add_f32_e32 v219, v0, v219
	v_add_f32_e32 v219, v177, v219
	v_cvt_pk_fp8_f32 v251, v0, v177
	v_add_f32_e32 v219, v179, v219
	v_add_f32_e32 v219, v254, v219
	v_cvt_pk_fp8_f32 v251, v179, v254 op_sel:[0,0,1]
	v_exp_f32_e32 v0, v106
	v_exp_f32_e32 v177, v107
	v_exp_f32_e32 v179, v108
	v_exp_f32_e32 v254, v109
	v_add_f32_e32 v219, v0, v219
	v_add_f32_e32 v219, v177, v219
	v_cvt_pk_fp8_f32 v252, v0, v177
	v_add_f32_e32 v219, v179, v219
	v_add_f32_e32 v219, v254, v219
	v_cvt_pk_fp8_f32 v252, v179, v254 op_sel:[0,0,1]
	s_waitcnt lgkmcnt(2)
	v_mfma_scale_f32_32x32x64_f8f6f4 v[82:97], v[122:129], v[130:137], v[82:97], v194, v193 op_sel_hi:[0,0,0]
	v_exp_f32_e32 v0, v110
	v_exp_f32_e32 v177, v111
	v_exp_f32_e32 v179, v112
	v_exp_f32_e32 v254, v113
	v_add_f32_e32 v219, v0, v219
	v_add_f32_e32 v219, v177, v219
	v_cvt_pk_fp8_f32 v253, v0, v177
	v_add_f32_e32 v219, v179, v219
	v_add_f32_e32 v219, v254, v219
	v_cvt_pk_fp8_f32 v253, v179, v254 op_sel:[0,0,1]
	ds_read_b128 v[122:125], v185 offset:0
	ds_read_b128 v[126:129], v186 offset:0
	ds_read_b128 v[114:117], v185 offset:2048
	ds_read_b128 v[118:121], v186 offset:2048
	ds_read_b128 v[106:109], v185 offset:4096
	ds_read_b128 v[110:113], v186 offset:4096
	ds_read_b128 v[98:101], v185 offset:6144
	ds_read_b128 v[102:105], v186 offset:6144
	s_waitcnt lgkmcnt(8)
	v_mfma_scale_f32_32x32x64_f8f6f4 v[66:81], v[222:229], v[130:137], v[66:81], v194, v193 op_sel_hi:[0,0,0]
	v_mov_b32_e32 v0, v219
	s_nop 1
	v_permlane32_swap_b32_e32 v219, v0
	v_add_f32_e32 v219, v219, v0
	v_fma_f32 v209, v209, v221, v219
	v_max_f32_e32 v177, v82, v83
	v_max3_f32 v177, v177, v84, v85
	v_max3_f32 v177, v177, v86, v87
	v_max3_f32 v177, v177, v88, v89
	v_max3_f32 v177, v177, v90, v91
	v_max3_f32 v177, v177, v92, v93
	v_max3_f32 v177, v177, v94, v95
	v_max3_f32 v177, v177, v96, v97
	s_waitcnt lgkmcnt(6)
	v_mfma_scale_f32_32x32x64_f8f6f4 v[50:65], v[246:253], v[122:129], v[50:65], v194, v194 op_sel_hi:[0,0,0]
	v_max_f32_e32 v0, v66, v67
	v_max3_f32 v0, v0, v68, v69
	v_max3_f32 v0, v0, v70, v71
	s_waitcnt vmcnt(0)
	ds_write_b128 v210, v[158:161] offset:43008
	ds_write_b128 v211, v[162:165] offset:51200
	s_waitcnt lgkmcnt(6)
	v_mfma_scale_f32_32x32x64_f8f6f4 v[34:49], v[246:253], v[114:121], v[34:49], v194, v194 op_sel_hi:[0,0,0]
	s_waitcnt lgkmcnt(0)
	s_barrier
	global_load_dwordx4 v[158:161], v176, s[18:19]
	global_load_dwordx4 v[162:165], v178, s[16:17]
	v_add_u32_e32 v176, 0x2000, v176
	v_add_u32_e32 v178, 0x20000, v178
	v_max3_f32 v0, v0, v72, v73
	v_max3_f32 v0, v0, v74, v75
	v_max3_f32 v0, v0, v76, v77
	s_waitcnt lgkmcnt(2)
	v_mfma_scale_f32_32x32x64_f8f6f4 v[18:33], v[246:253], v[106:113], v[18:33], v194, v194 op_sel_hi:[0,0,0]
	v_max3_f32 v0, v0, v78, v79
	v_max3_f32 v0, v0, v80, v81
	v_max_f32_e32 v177, v177, v0
	v_mov_b32_e32 v0, v177
	v_mov_b32_e32 v218, 1.0
	s_waitcnt lgkmcnt(0)
	v_mfma_scale_f32_32x32x64_f8f6f4 v[2:17], v[246:253], v[98:105], v[2:17], v194, v194 op_sel_hi:[0,0,0]
	s_nop 0
	v_permlane32_swap_b32_e32 v177, v0
	v_max_f32_e32 v177, v177, v0
	v_cmp_ge_f32_e32 vcc, s90, v177
	s_cmp_eq_u64 vcc, exec
	s_cbranch_scc0 .Lmla_s3_newmax
; __device__ __forceinline__ void finishSM9(f32x16& p0, f32x16& p1, float alpha, float& l_reg, v8i32& p8) {
; #pragma unroll
;   for (int r = 0; r < 16; ++r) { p0[r] = __builtin_amdgcn_exp2f(p0[r]); p1[r] = __builtin_amdgcn_exp2f(p1[r]); }
;   float ps = 0;
; #pragma unroll
;   for (int r = 0; r < 16; ++r) ps += p0[r];
; #pragma unroll
;   for (int r = 0; r < 16; ++r) ps += p1[r];
;   { auto rr = __builtin_amdgcn_permlane32_swap(__float_as_uint(ps), __float_as_uint(ps), false, false);
;     ps = __uint_as_float(rr[0]) + __uint_as_float(rr[1]); }
;   l_reg = l_reg * alpha + ps;
; #pragma unroll
;   for (int g = 0; g < 4; ++g) {
;     int w = __builtin_amdgcn_cvt_pk_fp8_f32(p0[4 * g], p0[4 * g + 1], 0, false); p8[g] = __builtin_amdgcn_cvt_pk_fp8_f32(p0[4 * g + 2], p0[4 * g + 3], w, true);
;     int u = __builtin_amdgcn_cvt_pk_fp8_f32(p1[4 * g], p1[4 * g + 1], 0, false); p8[4 + g] = __builtin_amdgcn_cvt_pk_fp8_f32(p1[4 * g + 2], p1[4 * g + 3], u, true); }
; }
; __device__ __forceinline__ void pv8(f32x16* o, const char* Vt, const v8i32 p8, int r32, int hi) {
;   const int sw = (r32 >> 2) & 3, a0 = r32 * 64 + (((hi * 2) ^ sw) << 4), a1 = r32 * 64 + (((hi * 2 + 1) ^ sw) << 4);
; #pragma unroll
;   for (int d0 = 0; d0 < 4; ++d0) {
;     const v8i32 vf = cat8(*reinterpret_cast<const v4i32*>(Vt + d0 * 2048 + a0), *reinterpret_cast<const v4i32*>(Vt + d0 * 2048 + a1));
;     o[d0] = __builtin_amdgcn_mfma_scale_f32_32x32x64_f8f6f4(p8, vf, o[d0], 0, 0, 0, 127, 0, 127); }
; }
; __device__ __forceinline__ void qkt9(f32x16& p0, f32x16& p1, const char* Kn, const char* Kr, const v8i32* qf, const float init, int r32, int hi) {
; #pragma unroll
;   for (int r = 0; r < 16; ++r) { p0[r] = init; p1[r] = init; }
; #pragma unroll
;   for (int s = 0; s < 2; ++s) { const int c0 = s * 4 + hi * 2;
;     const v8i32 a0 = cat8(*reinterpret_cast<const v4i32*>(Kn + KN8SW(r32, c0)), *reinterpret_cast<const v4i32*>(Kn + KN8SW(r32, c0 + 1)));
;     const v8i32 a1 = cat8(*reinterpret_cast<const v4i32*>(Kn + 4096 + KN8SW(r32, c0)), *reinterpret_cast<const v4i32*>(Kn + 4096 + KN8SW(r32, c0 + 1)));
;     p0 = __builtin_amdgcn_mfma_scale_f32_32x32x64_f8f6f4(a0, qf[s], p0, 0, 0, 0, 127, 0, 124);
;     p1 = __builtin_amdgcn_mfma_scale_f32_32x32x64_f8f6f4(a1, qf[s], p1, 0, 0, 0, 127, 0, 124); }
;   { const int c0 = hi * 2;
.Lmla_s3_cont:
	ds_read_b128 v[114:117], v215 offset:51200
	ds_read_b128 v[118:121], v216 offset:51200
	ds_read_b128 v[222:225], v215 offset:55296
	ds_read_b128 v[226:229], v216 offset:55296
	v_exp_f32_e32 v0, v82
	v_exp_f32_e32 v177, v83
	v_exp_f32_e32 v179, v84
	v_exp_f32_e32 v254, v85
	v_add_f32_e32 v219, v0, v177
	v_cvt_pk_fp8_f32 v246, v0, v177
	v_add_f32_e32 v219, v179, v219
	v_add_f32_e32 v219, v254, v219
	v_cvt_pk_fp8_f32 v246, v179, v254 op_sel:[0,0,1]
	s_waitcnt lgkmcnt(2)
	v_mfma_scale_f32_32x32x64_f8f6f4 v[114:129], v[114:121], v[146:153], v[230:245], v194, v193 op_sel_hi:[0,0,0]
	v_exp_f32_e32 v0, v86
	v_exp_f32_e32 v177, v87
	v_exp_f32_e32 v179, v88
	v_exp_f32_e32 v254, v89
	v_add_f32_e32 v219, v0, v219
	v_add_f32_e32 v219, v177, v219
	v_cvt_pk_fp8_f32 v247, v0, v177
	v_add_f32_e32 v219, v179, v219
	v_add_f32_e32 v219, v254, v219
	v_cvt_pk_fp8_f32 v247, v179, v254 op_sel:[0,0,1]
	ds_read_b128 v[82:85], v213 offset:51200
	ds_read_b128 v[86:89], v214 offset:51200
	s_waitcnt lgkmcnt(2)
	v_mfma_scale_f32_32x32x64_f8f6f4 v[98:113], v[222:229], v[146:153], v[230:245], v194, v193 op_sel_hi:[0,0,0]
	ds_read_b128 v[222:225], v213 offset:55296
	ds_read_b128 v[226:229], v214 offset:55296
	v_exp_f32_e32 v0, v90
	v_exp_f32_e32 v177, v91
	v_exp_f32_e32 v179, v92
	v_exp_f32_e32 v254, v93
	v_add_f32_e32 v219, v0, v219
	v_add_f32_e32 v219, v177, v219
	v_cvt_pk_fp8_f32 v248, v0, v177
	v_add_f32_e32 v219, v179, v219
	v_add_f32_e32 v219, v254, v219
	v_cvt_pk_fp8_f32 v248, v179, v254 op_sel:[0,0,1]
	v_exp_f32_e32 v0, v94
	v_exp_f32_e32 v177, v95
	v_exp_f32_e32 v179, v96
	v_exp_f32_e32 v254, v97
	v_add_f32_e32 v219, v0, v219
	v_add_f32_e32 v219, v177, v219
	v_cvt_pk_fp8_f32 v249, v0, v177
	v_add_f32_e32 v219, v179, v219
	v_add_f32_e32 v219, v254, v219
	v_cvt_pk_fp8_f32 v249, v179, v254 op_sel:[0,0,1]
	ds_read_b128 v[90:93], v185 offset:59392
	ds_read_b128 v[94:97], v186 offset:59392
	s_waitcnt lgkmcnt(4)
	v_mfma_scale_f32_32x32x64_f8f6f4 v[114:129], v[82:89], v[138:145], v[114:129], v194, v193 op_sel_hi:[0,0,0]
	v_exp_f32_e32 v0, v66
	v_exp_f32_e32 v177, v67
	v_exp_f32_e32 v179, v68
	v_exp_f32_e32 v254, v69
	v_add_f32_e32 v219, v0, v219
	v_add_f32_e32 v219, v177, v219
	v_cvt_pk_fp8_f32 v250, v0, v177
	v_add_f32_e32 v219, v179, v219
	v_add_f32_e32 v219, v254, v219
	v_cvt_pk_fp8_f32 v250, v179, v254 op_sel:[0,0,1]
	s_waitcnt lgkmcnt(2)
	v_mfma_scale_f32_32x32x64_f8f6f4 v[98:113], v[222:229], v[138:145], v[98:113], v194, v193 op_sel_hi:[0,0,0]
	ds_read_b128 v[222:225], v185 offset:61440
	ds_read_b128 v[226:229], v186 offset:61440
	v_exp_f32_e32 v0, v70
	v_exp_f32_e32 v177, v71
	v_exp_f32_e32 v179, v72
	v_exp_f32_e32 v254, v73
	v_add_f32_e32 v219, v0, v219
	v_add_f32_e32 v219, v177, v219
	v_cvt_pk_fp8_f32 v251, v0, v177
	v_add_f32_e32 v219, v179, v219
	v_add_f32_e32 v219, v254, v219
	v_cvt_pk_fp8_f32 v251, v179, v254 op_sel:[0,0,1]
	v_exp_f32_e32 v0, v74
	v_exp_f32_e32 v177, v75
	v_exp_f32_e32 v179, v76
	v_exp_f32_e32 v254, v77
	v_add_f32_e32 v219, v0, v219
	v_add_f32_e32 v219, v177, v219
	v_cvt_pk_fp8_f32 v252, v0, v177
	v_add_f32_e32 v219, v179, v219
	v_add_f32_e32 v219, v254, v219
	v_cvt_pk_fp8_f32 v252, v179, v254 op_sel:[0,0,1]
	s_waitcnt lgkmcnt(2)
	v_mfma_scale_f32_32x32x64_f8f6f4 v[114:129], v[90:97], v[130:137], v[114:129], v194, v193 op_sel_hi:[0,0,0]
	v_exp_f32_e32 v0, v78
	v_exp_f32_e32 v177, v79
	v_exp_f32_e32 v179, v80
	v_exp_f32_e32 v254, v81
	v_add_f32_e32 v219, v0, v219
	v_add_f32_e32 v219, v177, v219
	v_cvt_pk_fp8_f32 v253, v0, v177
	v_add_f32_e32 v219, v179, v219
	v_add_f32_e32 v219, v254, v219
	v_cvt_pk_fp8_f32 v253, v179, v254 op_sel:[0,0,1]
	ds_read_b128 v[90:93], v185 offset:8192
	ds_read_b128 v[94:97], v186 offset:8192
	ds_read_b128 v[82:85], v185 offset:10240
	ds_read_b128 v[86:89], v186 offset:10240
	ds_read_b128 v[74:77], v185 offset:12288
	ds_read_b128 v[78:81], v186 offset:12288
	ds_read_b128 v[66:69], v185 offset:14336
	ds_read_b128 v[70:73], v186 offset:14336
	s_waitcnt lgkmcnt(8)
	v_mfma_scale_f32_32x32x64_f8f6f4 v[98:113], v[222:229], v[130:137], v[98:113], v194, v193 op_sel_hi:[0,0,0]
	v_mov_b32_e32 v0, v219
	s_nop 1
	v_permlane32_swap_b32_e32 v219, v0
	v_add_f32_e32 v219, v219, v0
	v_fma_f32 v209, v209, v218, v219
	v_max_f32_e32 v177, v114, v115
	v_max3_f32 v177, v177, v116, v117
	v_max3_f32 v177, v177, v118, v119
	v_max3_f32 v177, v177, v120, v121
	v_max3_f32 v177, v177, v122, v123
	v_max3_f32 v177, v177, v124, v125
	v_max3_f32 v177, v177, v126, v127
	v_max3_f32 v177, v177, v128, v129
	s_waitcnt lgkmcnt(6)
	v_mfma_scale_f32_32x32x64_f8f6f4 v[50:65], v[246:253], v[90:97], v[50:65], v194, v194 op_sel_hi:[0,0,0]
	v_max_f32_e32 v0, v98, v99
	v_max3_f32 v0, v0, v100, v101
	v_max3_f32 v0, v0, v102, v103
	s_waitcnt vmcnt(0)
	ds_write_b128 v210, v[158:161]
	ds_write_b128 v211, v[162:165] offset:16384
	s_waitcnt lgkmcnt(6)
	v_mfma_scale_f32_32x32x64_f8f6f4 v[34:49], v[246:253], v[82:89], v[34:49], v194, v194 op_sel_hi:[0,0,0]
	s_waitcnt lgkmcnt(0)
	s_barrier
	global_load_dwordx4 v[158:161], v176, s[18:19]
	global_load_dwordx4 v[162:165], v178, s[16:17]
	v_add_u32_e32 v176, 0x2000, v176
	v_add_u32_e32 v178, 0x20000, v178
	v_max3_f32 v0, v0, v104, v105
	v_max3_f32 v0, v0, v106, v107
	v_max3_f32 v0, v0, v108, v109
	s_waitcnt lgkmcnt(2)
	v_mfma_scale_f32_32x32x64_f8f6f4 v[18:33], v[246:253], v[74:81], v[18:33], v194, v194 op_sel_hi:[0,0,0]
	v_max3_f32 v0, v0, v110, v111
	v_max3_f32 v0, v0, v112, v113
	v_max_f32_e32 v177, v177, v0
	v_mov_b32_e32 v0, v177
	v_mov_b32_e32 v221, 1.0
	s_waitcnt lgkmcnt(0)
	v_mfma_scale_f32_32x32x64_f8f6f4 v[2:17], v[246:253], v[66:73], v[2:17], v194, v194 op_sel_hi:[0,0,0]
	s_nop 0
	v_permlane32_swap_b32_e32 v177, v0
	v_max_f32_e32 v177, v177, v0
	v_cmp_ge_f32_e32 vcc, s90, v177
	s_cmp_eq_u64 vcc, exec
	s_cbranch_scc0 .Lmla_s4_newmax
; __device__ __forceinline__ void finishSM9(f32x16& p0, f32x16& p1, float alpha, float& l_reg, v8i32& p8) {
; #pragma unroll
;   for (int r = 0; r < 16; ++r) { p0[r] = __builtin_amdgcn_exp2f(p0[r]); p1[r] = __builtin_amdgcn_exp2f(p1[r]); }
;   float ps = 0;
; #pragma unroll
;   for (int r = 0; r < 16; ++r) ps += p0[r];
; #pragma unroll
;   for (int r = 0; r < 16; ++r) ps += p1[r];
;   { auto rr = __builtin_amdgcn_permlane32_swap(__float_as_uint(ps), __float_as_uint(ps), false, false);
;     ps = __uint_as_float(rr[0]) + __uint_as_float(rr[1]); }
;   l_reg = l_reg * alpha + ps;
; #pragma unroll
;   for (int g = 0; g < 4; ++g) {
;     int w = __builtin_amdgcn_cvt_pk_fp8_f32(p0[4 * g], p0[4 * g + 1], 0, false); p8[g] = __builtin_amdgcn_cvt_pk_fp8_f32(p0[4 * g + 2], p0[4 * g + 3], w, true);
;     int u = __builtin_amdgcn_cvt_pk_fp8_f32(p1[4 * g], p1[4 * g + 1], 0, false); p8[4 + g] = __builtin_amdgcn_cvt_pk_fp8_f32(p1[4 * g + 2], p1[4 * g + 3], u, true); }
; }
; __device__ __forceinline__ void pv8(f32x16* o, const char* Vt, const v8i32 p8, int r32, int hi) {
;   const int sw = (r32 >> 2) & 3, a0 = r32 * 64 + (((hi * 2) ^ sw) << 4), a1 = r32 * 64 + (((hi * 2 + 1) ^ sw) << 4);
; #pragma unroll
;   for (int d0 = 0; d0 < 4; ++d0) {
;     const v8i32 vf = cat8(*reinterpret_cast<const v4i32*>(Vt + d0 * 2048 + a0), *reinterpret_cast<const v4i32*>(Vt + d0 * 2048 + a1));
;     o[d0] = __builtin_amdgcn_mfma_scale_f32_32x32x64_f8f6f4(p8, vf, o[d0], 0, 0, 0, 127, 0, 127); }
; }
; __device__ __forceinline__ void qkt9(f32x16& p0, f32x16& p1, const char* Kn, const char* Kr, const v8i32* qf, const float init, int r32, int hi) {
; #pragma unroll
;   for (int r = 0; r < 16; ++r) { p0[r] = init; p1[r] = init; }
; #pragma unroll
;   for (int s = 0; s < 2; ++s) { const int c0 = s * 4 + hi * 2;
;     const v8i32 a0 = cat8(*reinterpret_cast<const v4i32*>(Kn + KN8SW(r32, c0)), *reinterpret_cast<const v4i32*>(Kn + KN8SW(r32, c0 + 1)));
;     const v8i32 a1 = cat8(*reinterpret_cast<const v4i32*>(Kn + 4096 + KN8SW(r32, c0)), *reinterpret_cast<const v4i32*>(Kn + 4096 + KN8SW(r32, c0 + 1)));
;     p0 = __builtin_amdgcn_mfma_scale_f32_32x32x64_f8f6f4(a0, qf[s], p0, 0, 0, 0, 127, 0, 124);
;     p1 = __builtin_amdgcn_mfma_scale_f32_32x32x64_f8f6f4(a1, qf[s], p1, 0, 0, 0, 127, 0, 124); }
;   { const int c0 = hi * 2;
.Lmla_s4_cont:
	ds_read_b128 v[82:85], v215 offset:16384
	ds_read_b128 v[86:89], v216 offset:16384
	ds_read_b128 v[222:225], v215 offset:20480
	ds_read_b128 v[226:229], v216 offset:20480
	v_exp_f32_e32 v0, v114
	v_exp_f32_e32 v177, v115
	v_exp_f32_e32 v179, v116
	v_exp_f32_e32 v254, v117
	v_add_f32_e32 v219, v0, v177
	v_cvt_pk_fp8_f32 v246, v0, v177
	v_add_f32_e32 v219, v179, v219
	v_add_f32_e32 v219, v254, v219
	v_cvt_pk_fp8_f32 v246, v179, v254 op_sel:[0,0,1]
	s_waitcnt lgkmcnt(2)
	v_mfma_scale_f32_32x32x64_f8f6f4 v[82:97], v[82:89], v[146:153], v[230:245], v194, v193 op_sel_hi:[0,0,0]
	v_exp_f32_e32 v0, v118
	v_exp_f32_e32 v177, v119
	v_exp_f32_e32 v179, v120
	v_exp_f32_e32 v254, v121
	v_add_f32_e32 v219, v0, v219
	v_add_f32_e32 v219, v177, v219
	v_cvt_pk_fp8_f32 v247, v0, v177
	v_add_f32_e32 v219, v179, v219
	v_add_f32_e32 v219, v254, v219
	v_cvt_pk_fp8_f32 v247, v179, v254 op_sel:[0,0,1]
	ds_read_b128 v[114:117], v213 offset:16384
	ds_read_b128 v[118:121], v214 offset:16384
	s_waitcnt lgkmcnt(2)
	v_mfma_scale_f32_32x32x64_f8f6f4 v[66:81], v[222:229], v[146:153], v[230:245], v194, v193 op_sel_hi:[0,0,0]
	ds_read_b128 v[222:225], v213 offset:20480
	ds_read_b128 v[226:229], v214 offset:20480
	v_exp_f32_e32 v0, v122
	v_exp_f32_e32 v177, v123
	v_exp_f32_e32 v179, v124
	v_exp_f32_e32 v254, v125
	v_add_f32_e32 v219, v0, v219
	v_add_f32_e32 v219, v177, v219
	v_cvt_pk_fp8_f32 v248, v0, v177
	v_add_f32_e32 v219, v179, v219
	v_add_f32_e32 v219, v254, v219
	v_cvt_pk_fp8_f32 v248, v179, v254 op_sel:[0,0,1]
	v_exp_f32_e32 v0, v126
	v_exp_f32_e32 v177, v127
	v_exp_f32_e32 v179, v128
	v_exp_f32_e32 v254, v129
	v_add_f32_e32 v219, v0, v219
	v_add_f32_e32 v219, v177, v219
	v_cvt_pk_fp8_f32 v249, v0, v177
	v_add_f32_e32 v219, v179, v219
	v_add_f32_e32 v219, v254, v219
	v_cvt_pk_fp8_f32 v249, v179, v254 op_sel:[0,0,1]
	ds_read_b128 v[122:125], v185 offset:32768
	ds_read_b128 v[126:129], v186 offset:32768
	s_waitcnt lgkmcnt(4)
	v_mfma_scale_f32_32x32x64_f8f6f4 v[82:97], v[114:121], v[138:145], v[82:97], v194, v193 op_sel_hi:[0,0,0]
	v_exp_f32_e32 v0, v98
	v_exp_f32_e32 v177, v99
	v_exp_f32_e32 v179, v100
	v_exp_f32_e32 v254, v101
	v_add_f32_e32 v219, v0, v219
	v_add_f32_e32 v219, v177, v219
	v_cvt_pk_fp8_f32 v250, v0, v177
	v_add_f32_e32 v219, v179, v219
	v_add_f32_e32 v219, v254, v219
	v_cvt_pk_fp8_f32 v250, v179, v254 op_sel:[0,0,1]
	s_waitcnt lgkmcnt(2)
	v_mfma_scale_f32_32x32x64_f8f6f4 v[66:81], v[222:229], v[138:145], v[66:81], v194, v193 op_sel_hi:[0,0,0]
	ds_read_b128 v[222:225], v185 offset:34816
	ds_read_b128 v[226:229], v186 offset:34816
	v_exp_f32_e32 v0, v102
	v_exp_f32_e32 v177, v103
	v_exp_f32_e32 v179, v104
	v_exp_f32_e32 v254, v105
	v_add_f32_e32 v219, v0, v219
	v_add_f32_e32 v219, v177, v219
	v_cvt_pk_fp8_f32 v251, v0, v177
	v_add_f32_e32 v219, v179, v219
	v_add_f32_e32 v219, v254, v219
	v_cvt_pk_fp8_f32 v251, v179, v254 op_sel:[0,0,1]
	v_exp_f32_e32 v0, v106
	v_exp_f32_e32 v177, v107
	v_exp_f32_e32 v179, v108
	v_exp_f32_e32 v254, v109
	v_add_f32_e32 v219, v0, v219
	v_add_f32_e32 v219, v177, v219
	v_cvt_pk_fp8_f32 v252, v0, v177
	v_add_f32_e32 v219, v179, v219
	v_add_f32_e32 v219, v254, v219
	v_cvt_pk_fp8_f32 v252, v179, v254 op_sel:[0,0,1]
	s_waitcnt lgkmcnt(2)
	v_mfma_scale_f32_32x32x64_f8f6f4 v[82:97], v[122:129], v[130:137], v[82:97], v194, v193 op_sel_hi:[0,0,0]
	v_exp_f32_e32 v0, v110
	v_exp_f32_e32 v177, v111
	v_exp_f32_e32 v179, v112
	v_exp_f32_e32 v254, v113
	v_add_f32_e32 v219, v0, v219
	v_add_f32_e32 v219, v177, v219
	v_cvt_pk_fp8_f32 v253, v0, v177
	v_add_f32_e32 v219, v179, v219
	v_add_f32_e32 v219, v254, v219
	v_cvt_pk_fp8_f32 v253, v179, v254 op_sel:[0,0,1]
	ds_read_b128 v[122:125], v185 offset:43008
	ds_read_b128 v[126:129], v186 offset:43008
	ds_read_b128 v[114:117], v185 offset:45056
	ds_read_b128 v[118:121], v186 offset:45056
	ds_read_b128 v[106:109], v185 offset:47104
	ds_read_b128 v[110:113], v186 offset:47104
	ds_read_b128 v[98:101], v185 offset:49152
	ds_read_b128 v[102:105], v186 offset:49152
	s_waitcnt lgkmcnt(8)
	v_mfma_scale_f32_32x32x64_f8f6f4 v[66:81], v[222:229], v[130:137], v[66:81], v194, v193 op_sel_hi:[0,0,0]
	v_mov_b32_e32 v0, v219
	s_nop 1
	v_permlane32_swap_b32_e32 v219, v0
	v_add_f32_e32 v219, v219, v0
	v_fma_f32 v209, v209, v221, v219
	v_max_f32_e32 v177, v82, v83
	v_max3_f32 v177, v177, v84, v85
	v_max3_f32 v177, v177, v86, v87
	v_max3_f32 v177, v177, v88, v89
	v_max3_f32 v177, v177, v90, v91
	v_max3_f32 v177, v177, v92, v93
	v_max3_f32 v177, v177, v94, v95
	v_max3_f32 v177, v177, v96, v97
	s_waitcnt lgkmcnt(6)
	v_mfma_scale_f32_32x32x64_f8f6f4 v[50:65], v[246:253], v[122:129], v[50:65], v194, v194 op_sel_hi:[0,0,0]
	v_max_f32_e32 v0, v66, v67
	v_max3_f32 v0, v0, v68, v69
	v_max3_f32 v0, v0, v70, v71
	s_waitcnt vmcnt(0)
	ds_write_b128 v210, v[158:161] offset:8192
	ds_write_b128 v211, v[162:165] offset:24576
	s_waitcnt lgkmcnt(6)
	v_mfma_scale_f32_32x32x64_f8f6f4 v[34:49], v[246:253], v[114:121], v[34:49], v194, v194 op_sel_hi:[0,0,0]
	s_waitcnt lgkmcnt(0)
	s_barrier
	global_load_dwordx4 v[158:161], v176, s[18:19]
	global_load_dwordx4 v[162:165], v178, s[16:17]
	v_add_u32_e32 v176, 0x2000, v176
	v_add_u32_e32 v178, 0x20000, v178
	v_max3_f32 v0, v0, v72, v73
	v_max3_f32 v0, v0, v74, v75
	v_max3_f32 v0, v0, v76, v77
	s_waitcnt lgkmcnt(2)
	v_mfma_scale_f32_32x32x64_f8f6f4 v[18:33], v[246:253], v[106:113], v[18:33], v194, v194 op_sel_hi:[0,0,0]
	v_max3_f32 v0, v0, v78, v79
	v_max3_f32 v0, v0, v80, v81
	v_max_f32_e32 v177, v177, v0
	v_mov_b32_e32 v0, v177
	v_mov_b32_e32 v218, 1.0
	s_waitcnt lgkmcnt(0)
	v_mfma_scale_f32_32x32x64_f8f6f4 v[2:17], v[246:253], v[98:105], v[2:17], v194, v194 op_sel_hi:[0,0,0]
	s_nop 0
	v_permlane32_swap_b32_e32 v177, v0
	v_max_f32_e32 v177, v177, v0
	v_cmp_ge_f32_e32 vcc, s90, v177
	s_cmp_eq_u64 vcc, exec
	s_cbranch_scc0 .Lmla_s5_newmax
; __device__ __forceinline__ void finishSM9(f32x16& p0, f32x16& p1, float alpha, float& l_reg, v8i32& p8) {
; #pragma unroll
;   for (int r = 0; r < 16; ++r) { p0[r] = __builtin_amdgcn_exp2f(p0[r]); p1[r] = __builtin_amdgcn_exp2f(p1[r]); }
;   float ps = 0;
; #pragma unroll
;   for (int r = 0; r < 16; ++r) ps += p0[r];
; #pragma unroll
;   for (int r = 0; r < 16; ++r) ps += p1[r];
;   { auto rr = __builtin_amdgcn_permlane32_swap(__float_as_uint(ps), __float_as_uint(ps), false, false);
;     ps = __uint_as_float(rr[0]) + __uint_as_float(rr[1]); }
;   l_reg = l_reg * alpha + ps;
; #pragma unroll
;   for (int g = 0; g < 4; ++g) {
;     int w = __builtin_amdgcn_cvt_pk_fp8_f32(p0[4 * g], p0[4 * g + 1], 0, false); p8[g] = __builtin_amdgcn_cvt_pk_fp8_f32(p0[4 * g + 2], p0[4 * g + 3], w, true);
;     int u = __builtin_amdgcn_cvt_pk_fp8_f32(p1[4 * g], p1[4 * g + 1], 0, false); p8[4 + g] = __builtin_amdgcn_cvt_pk_fp8_f32(p1[4 * g + 2], p1[4 * g + 3], u, true); }
; }
; __device__ __forceinline__ void pv8(f32x16* o, const char* Vt, const v8i32 p8, int r32, int hi) {
;   const int sw = (r32 >> 2) & 3, a0 = r32 * 64 + (((hi * 2) ^ sw) << 4), a1 = r32 * 64 + (((hi * 2 + 1) ^ sw) << 4);
; #pragma unroll
;   for (int d0 = 0; d0 < 4; ++d0) {
;     const v8i32 vf = cat8(*reinterpret_cast<const v4i32*>(Vt + d0 * 2048 + a0), *reinterpret_cast<const v4i32*>(Vt + d0 * 2048 + a1));
;     o[d0] = __builtin_amdgcn_mfma_scale_f32_32x32x64_f8f6f4(p8, vf, o[d0], 0, 0, 0, 127, 0, 127); }
; }
; __device__ __forceinline__ void qkt9(f32x16& p0, f32x16& p1, const char* Kn, const char* Kr, const v8i32* qf, const float init, int r32, int hi) {
; #pragma unroll
;   for (int r = 0; r < 16; ++r) { p0[r] = init; p1[r] = init; }
; #pragma unroll
;   for (int s = 0; s < 2; ++s) { const int c0 = s * 4 + hi * 2;
;     const v8i32 a0 = cat8(*reinterpret_cast<const v4i32*>(Kn + KN8SW(r32, c0)), *reinterpret_cast<const v4i32*>(Kn + KN8SW(r32, c0 + 1)));
;     const v8i32 a1 = cat8(*reinterpret_cast<const v4i32*>(Kn + 4096 + KN8SW(r32, c0)), *reinterpret_cast<const v4i32*>(Kn + 4096 + KN8SW(r32, c0 + 1)));
;     p0 = __builtin_amdgcn_mfma_scale_f32_32x32x64_f8f6f4(a0, qf[s], p0, 0, 0, 0, 127, 0, 124);
;     p1 = __builtin_amdgcn_mfma_scale_f32_32x32x64_f8f6f4(a1, qf[s], p1, 0, 0, 0, 127, 0, 124); }
;   { const int c0 = hi * 2;
.Lmla_s5_cont:
	s_add_i32 s30, s30, 1
	s_cmpk_lt_u32 s30, 42
	s_cbranch_scc1 .Lmla_stag_loop
	ds_read_b128 v[114:117], v215 offset:24576
	ds_read_b128 v[118:121], v216 offset:24576
	ds_read_b128 v[222:225], v215 offset:28672
	ds_read_b128 v[226:229], v216 offset:28672
	v_exp_f32_e32 v0, v82
	v_exp_f32_e32 v177, v83
	v_exp_f32_e32 v179, v84
	v_exp_f32_e32 v254, v85
	v_add_f32_e32 v219, v0, v177
	v_cvt_pk_fp8_f32 v246, v0, v177
	v_add_f32_e32 v219, v179, v219
	v_add_f32_e32 v219, v254, v219
	v_cvt_pk_fp8_f32 v246, v179, v254 op_sel:[0,0,1]
	s_waitcnt lgkmcnt(2)
	v_mfma_scale_f32_32x32x64_f8f6f4 v[114:129], v[114:121], v[146:153], v[230:245], v194, v193 op_sel_hi:[0,0,0]
	v_exp_f32_e32 v0, v86
	v_exp_f32_e32 v177, v87
	v_exp_f32_e32 v179, v88
	v_exp_f32_e32 v254, v89
	v_add_f32_e32 v219, v0, v219
	v_add_f32_e32 v219, v177, v219
	v_cvt_pk_fp8_f32 v247, v0, v177
	v_add_f32_e32 v219, v179, v219
	v_add_f32_e32 v219, v254, v219
	v_cvt_pk_fp8_f32 v247, v179, v254 op_sel:[0,0,1]
	ds_read_b128 v[82:85], v213 offset:24576
	ds_read_b128 v[86:89], v214 offset:24576
	s_waitcnt lgkmcnt(2)
	v_mfma_scale_f32_32x32x64_f8f6f4 v[98:113], v[222:229], v[146:153], v[230:245], v194, v193 op_sel_hi:[0,0,0]
	ds_read_b128 v[222:225], v213 offset:28672
	ds_read_b128 v[226:229], v214 offset:28672
	v_exp_f32_e32 v0, v90
	v_exp_f32_e32 v177, v91
	v_exp_f32_e32 v179, v92
	v_exp_f32_e32 v254, v93
	v_add_f32_e32 v219, v0, v219
	v_add_f32_e32 v219, v177, v219
	v_cvt_pk_fp8_f32 v248, v0, v177
	v_add_f32_e32 v219, v179, v219
	v_add_f32_e32 v219, v254, v219
	v_cvt_pk_fp8_f32 v248, v179, v254 op_sel:[0,0,1]
	v_exp_f32_e32 v0, v94
	v_exp_f32_e32 v177, v95
	v_exp_f32_e32 v179, v96
	v_exp_f32_e32 v254, v97
	v_add_f32_e32 v219, v0, v219
	v_add_f32_e32 v219, v177, v219
	v_cvt_pk_fp8_f32 v249, v0, v177
	v_add_f32_e32 v219, v179, v219
	v_add_f32_e32 v219, v254, v219
	v_cvt_pk_fp8_f32 v249, v179, v254 op_sel:[0,0,1]
	ds_read_b128 v[90:93], v185 offset:36864
	ds_read_b128 v[94:97], v186 offset:36864
	s_waitcnt lgkmcnt(4)
	v_mfma_scale_f32_32x32x64_f8f6f4 v[114:129], v[82:89], v[138:145], v[114:129], v194, v193 op_sel_hi:[0,0,0]
	v_exp_f32_e32 v0, v66
	v_exp_f32_e32 v177, v67
	v_exp_f32_e32 v179, v68
	v_exp_f32_e32 v254, v69
	v_add_f32_e32 v219, v0, v219
	v_add_f32_e32 v219, v177, v219
	v_cvt_pk_fp8_f32 v250, v0, v177
	v_add_f32_e32 v219, v179, v219
	v_add_f32_e32 v219, v254, v219
	v_cvt_pk_fp8_f32 v250, v179, v254 op_sel:[0,0,1]
	s_waitcnt lgkmcnt(2)
	v_mfma_scale_f32_32x32x64_f8f6f4 v[98:113], v[222:229], v[138:145], v[98:113], v194, v193 op_sel_hi:[0,0,0]
	ds_read_b128 v[222:225], v185 offset:38912
	ds_read_b128 v[226:229], v186 offset:38912
	v_exp_f32_e32 v0, v70
	v_exp_f32_e32 v177, v71
	v_exp_f32_e32 v179, v72
	v_exp_f32_e32 v254, v73
	v_add_f32_e32 v219, v0, v219
	v_add_f32_e32 v219, v177, v219
	v_cvt_pk_fp8_f32 v251, v0, v177
	v_add_f32_e32 v219, v179, v219
	v_add_f32_e32 v219, v254, v219
	v_cvt_pk_fp8_f32 v251, v179, v254 op_sel:[0,0,1]
	v_exp_f32_e32 v0, v74
	v_exp_f32_e32 v177, v75
	v_exp_f32_e32 v179, v76
	v_exp_f32_e32 v254, v77
	v_add_f32_e32 v219, v0, v219
	v_add_f32_e32 v219, v177, v219
	v_cvt_pk_fp8_f32 v252, v0, v177
	v_add_f32_e32 v219, v179, v219
	v_add_f32_e32 v219, v254, v219
	v_cvt_pk_fp8_f32 v252, v179, v254 op_sel:[0,0,1]
	s_waitcnt lgkmcnt(2)
	v_mfma_scale_f32_32x32x64_f8f6f4 v[114:129], v[90:97], v[130:137], v[114:129], v194, v193 op_sel_hi:[0,0,0]
	v_exp_f32_e32 v0, v78
	v_exp_f32_e32 v177, v79
	v_exp_f32_e32 v179, v80
	v_exp_f32_e32 v254, v81
	v_add_f32_e32 v219, v0, v219
	v_add_f32_e32 v219, v177, v219
	v_cvt_pk_fp8_f32 v253, v0, v177
	v_add_f32_e32 v219, v179, v219
	v_add_f32_e32 v219, v254, v219
	v_cvt_pk_fp8_f32 v253, v179, v254 op_sel:[0,0,1]
	ds_read_b128 v[90:93], v185 offset:0
	ds_read_b128 v[94:97], v186 offset:0
	ds_read_b128 v[82:85], v185 offset:2048
	ds_read_b128 v[86:89], v186 offset:2048
	ds_read_b128 v[74:77], v185 offset:4096
	ds_read_b128 v[78:81], v186 offset:4096
	ds_read_b128 v[66:69], v185 offset:6144
	ds_read_b128 v[70:73], v186 offset:6144
	s_waitcnt lgkmcnt(8)
	v_mfma_scale_f32_32x32x64_f8f6f4 v[98:113], v[222:229], v[130:137], v[98:113], v194, v193 op_sel_hi:[0,0,0]
	v_mov_b32_e32 v0, v219
	s_nop 1
	v_permlane32_swap_b32_e32 v219, v0
	v_add_f32_e32 v219, v219, v0
	v_fma_f32 v209, v209, v218, v219
	v_max_f32_e32 v177, v114, v115
	v_max3_f32 v177, v177, v116, v117
	v_max3_f32 v177, v177, v118, v119
	v_max3_f32 v177, v177, v120, v121
	v_max3_f32 v177, v177, v122, v123
	v_max3_f32 v177, v177, v124, v125
	v_max3_f32 v177, v177, v126, v127
	v_max3_f32 v177, v177, v128, v129
	s_waitcnt lgkmcnt(6)
	v_mfma_scale_f32_32x32x64_f8f6f4 v[50:65], v[246:253], v[90:97], v[50:65], v194, v194 op_sel_hi:[0,0,0]
	v_max_f32_e32 v0, v98, v99
	v_max3_f32 v0, v0, v100, v101
	v_max3_f32 v0, v0, v102, v103
	s_waitcnt vmcnt(0)
	ds_write_b128 v210, v[158:161] offset:43008
	ds_write_b128 v211, v[162:165] offset:51200
	s_waitcnt lgkmcnt(6)
	v_mfma_scale_f32_32x32x64_f8f6f4 v[34:49], v[246:253], v[82:89], v[34:49], v194, v194 op_sel_hi:[0,0,0]
	s_waitcnt lgkmcnt(0)
	s_barrier
	global_load_dwordx4 v[158:161], v176, s[18:19]
	global_load_dwordx4 v[162:165], v178, s[16:17]
	v_add_u32_e32 v176, 0x2000, v176
	v_add_u32_e32 v178, 0x20000, v178
	v_max3_f32 v0, v0, v104, v105
	v_max3_f32 v0, v0, v106, v107
	v_max3_f32 v0, v0, v108, v109
	s_waitcnt lgkmcnt(2)
	v_mfma_scale_f32_32x32x64_f8f6f4 v[18:33], v[246:253], v[74:81], v[18:33], v194, v194 op_sel_hi:[0,0,0]
	v_max3_f32 v0, v0, v110, v111
	v_max3_f32 v0, v0, v112, v113
	v_max_f32_e32 v177, v177, v0
	v_mov_b32_e32 v0, v177
	v_mov_b32_e32 v221, 1.0
	s_waitcnt lgkmcnt(0)
	v_mfma_scale_f32_32x32x64_f8f6f4 v[2:17], v[246:253], v[66:73], v[2:17], v194, v194 op_sel_hi:[0,0,0]
	s_nop 0
	v_permlane32_swap_b32_e32 v177, v0
	v_max_f32_e32 v177, v177, v0
	v_cmp_ge_f32_e32 vcc, s90, v177
	s_cmp_eq_u64 vcc, exec
	s_cbranch_scc0 .Lmla_q0_newmax
; __device__ __forceinline__ void finishSM9(f32x16& p0, f32x16& p1, float alpha, float& l_reg, v8i32& p8) {
; #pragma unroll
;   for (int r = 0; r < 16; ++r) { p0[r] = __builtin_amdgcn_exp2f(p0[r]); p1[r] = __builtin_amdgcn_exp2f(p1[r]); }
;   float ps = 0;
; #pragma unroll
;   for (int r = 0; r < 16; ++r) ps += p0[r];
; #pragma unroll
;   for (int r = 0; r < 16; ++r) ps += p1[r];
;   { auto rr = __builtin_amdgcn_permlane32_swap(__float_as_uint(ps), __float_as_uint(ps), false, false);
;     ps = __uint_as_float(rr[0]) + __uint_as_float(rr[1]); }
;   l_reg = l_reg * alpha + ps;
; #pragma unroll
;   for (int g = 0; g < 4; ++g) {
;     int w = __builtin_amdgcn_cvt_pk_fp8_f32(p0[4 * g], p0[4 * g + 1], 0, false); p8[g] = __builtin_amdgcn_cvt_pk_fp8_f32(p0[4 * g + 2], p0[4 * g + 3], w, true);
;     int u = __builtin_amdgcn_cvt_pk_fp8_f32(p1[4 * g], p1[4 * g + 1], 0, false); p8[4 + g] = __builtin_amdgcn_cvt_pk_fp8_f32(p1[4 * g + 2], p1[4 * g + 3], u, true); }
; }
; __device__ __forceinline__ void pv8(f32x16* o, const char* Vt, const v8i32 p8, int r32, int hi) {
;   const int sw = (r32 >> 2) & 3, a0 = r32 * 64 + (((hi * 2) ^ sw) << 4), a1 = r32 * 64 + (((hi * 2 + 1) ^ sw) << 4);
; #pragma unroll
;   for (int d0 = 0; d0 < 4; ++d0) {
;     const v8i32 vf = cat8(*reinterpret_cast<const v4i32*>(Vt + d0 * 2048 + a0), *reinterpret_cast<const v4i32*>(Vt + d0 * 2048 + a1));
;     o[d0] = __builtin_amdgcn_mfma_scale_f32_32x32x64_f8f6f4(p8, vf, o[d0], 0, 0, 0, 127, 0, 127); }
; }
; __device__ __forceinline__ void qkt9(f32x16& p0, f32x16& p1, const char* Kn, const char* Kr, const v8i32* qf, const float init, int r32, int hi) {
; #pragma unroll
;   for (int r = 0; r < 16; ++r) { p0[r] = init; p1[r] = init; }
; #pragma unroll
;   for (int s = 0; s < 2; ++s) { const int c0 = s * 4 + hi * 2;
;     const v8i32 a0 = cat8(*reinterpret_cast<const v4i32*>(Kn + KN8SW(r32, c0)), *reinterpret_cast<const v4i32*>(Kn + KN8SW(r32, c0 + 1)));
;     const v8i32 a1 = cat8(*reinterpret_cast<const v4i32*>(Kn + 4096 + KN8SW(r32, c0)), *reinterpret_cast<const v4i32*>(Kn + 4096 + KN8SW(r32, c0 + 1)));
;     p0 = __builtin_amdgcn_mfma_scale_f32_32x32x64_f8f6f4(a0, qf[s], p0, 0, 0, 0, 127, 0, 124);
;     p1 = __builtin_amdgcn_mfma_scale_f32_32x32x64_f8f6f4(a1, qf[s], p1, 0, 0, 0, 127, 0, 124); }
;   { const int c0 = hi * 2;
.Lmla_q0_cont:
	ds_read_b128 v[82:85], v215 offset:51200
	ds_read_b128 v[86:89], v216 offset:51200
	ds_read_b128 v[222:225], v215 offset:55296
	ds_read_b128 v[226:229], v216 offset:55296
	v_exp_f32_e32 v0, v114
	v_exp_f32_e32 v177, v115
	v_exp_f32_e32 v179, v116
	v_exp_f32_e32 v254, v117
	v_add_f32_e32 v219, v0, v177
	v_cvt_pk_fp8_f32 v246, v0, v177
	v_add_f32_e32 v219, v179, v219
	v_add_f32_e32 v219, v254, v219
	v_cvt_pk_fp8_f32 v246, v179, v254 op_sel:[0,0,1]
	s_waitcnt lgkmcnt(2)
	v_mfma_scale_f32_32x32x64_f8f6f4 v[82:97], v[82:89], v[146:153], v[230:245], v194, v193 op_sel_hi:[0,0,0]
	v_exp_f32_e32 v0, v118
	v_exp_f32_e32 v177, v119
	v_exp_f32_e32 v179, v120
	v_exp_f32_e32 v254, v121
	v_add_f32_e32 v219, v0, v219
	v_add_f32_e32 v219, v177, v219
	v_cvt_pk_fp8_f32 v247, v0, v177
	v_add_f32_e32 v219, v179, v219
	v_add_f32_e32 v219, v254, v219
	v_cvt_pk_fp8_f32 v247, v179, v254 op_sel:[0,0,1]
	ds_read_b128 v[114:117], v213 offset:51200
	ds_read_b128 v[118:121], v214 offset:51200
	s_waitcnt lgkmcnt(2)
	v_mfma_scale_f32_32x32x64_f8f6f4 v[66:81], v[222:229], v[146:153], v[230:245], v194, v193 op_sel_hi:[0,0,0]
	ds_read_b128 v[222:225], v213 offset:55296
	ds_read_b128 v[226:229], v214 offset:55296
	v_exp_f32_e32 v0, v122
	v_exp_f32_e32 v177, v123
	v_exp_f32_e32 v179, v124
	v_exp_f32_e32 v254, v125
	v_add_f32_e32 v219, v0, v219
	v_add_f32_e32 v219, v177, v219
	v_cvt_pk_fp8_f32 v248, v0, v177
	v_add_f32_e32 v219, v179, v219
	v_add_f32_e32 v219, v254, v219
	v_cvt_pk_fp8_f32 v248, v179, v254 op_sel:[0,0,1]
	v_exp_f32_e32 v0, v126
	v_exp_f32_e32 v177, v127
	v_exp_f32_e32 v179, v128
	v_exp_f32_e32 v254, v129
	v_add_f32_e32 v219, v0, v219
	v_add_f32_e32 v219, v177, v219
	v_cvt_pk_fp8_f32 v249, v0, v177
	v_add_f32_e32 v219, v179, v219
	v_add_f32_e32 v219, v254, v219
	v_cvt_pk_fp8_f32 v249, v179, v254 op_sel:[0,0,1]
	ds_read_b128 v[122:125], v185 offset:59392
	ds_read_b128 v[126:129], v186 offset:59392
	s_waitcnt lgkmcnt(4)
	v_mfma_scale_f32_32x32x64_f8f6f4 v[82:97], v[114:121], v[138:145], v[82:97], v194, v193 op_sel_hi:[0,0,0]
	v_exp_f32_e32 v0, v98
	v_exp_f32_e32 v177, v99
	v_exp_f32_e32 v179, v100
	v_exp_f32_e32 v254, v101
	v_add_f32_e32 v219, v0, v219
	v_add_f32_e32 v219, v177, v219
	v_cvt_pk_fp8_f32 v250, v0, v177
	v_add_f32_e32 v219, v179, v219
	v_add_f32_e32 v219, v254, v219
	v_cvt_pk_fp8_f32 v250, v179, v254 op_sel:[0,0,1]
	s_waitcnt lgkmcnt(2)
	v_mfma_scale_f32_32x32x64_f8f6f4 v[66:81], v[222:229], v[138:145], v[66:81], v194, v193 op_sel_hi:[0,0,0]
	ds_read_b128 v[222:225], v185 offset:61440
	ds_read_b128 v[226:229], v186 offset:61440
	v_exp_f32_e32 v0, v102
	v_exp_f32_e32 v177, v103
	v_exp_f32_e32 v179, v104
	v_exp_f32_e32 v254, v105
	v_add_f32_e32 v219, v0, v219
	v_add_f32_e32 v219, v177, v219
	v_cvt_pk_fp8_f32 v251, v0, v177
	v_add_f32_e32 v219, v179, v219
	v_add_f32_e32 v219, v254, v219
	v_cvt_pk_fp8_f32 v251, v179, v254 op_sel:[0,0,1]
	v_exp_f32_e32 v0, v106
	v_exp_f32_e32 v177, v107
	v_exp_f32_e32 v179, v108
	v_exp_f32_e32 v254, v109
	v_add_f32_e32 v219, v0, v219
	v_add_f32_e32 v219, v177, v219
	v_cvt_pk_fp8_f32 v252, v0, v177
	v_add_f32_e32 v219, v179, v219
	v_add_f32_e32 v219, v254, v219
	v_cvt_pk_fp8_f32 v252, v179, v254 op_sel:[0,0,1]
	s_waitcnt lgkmcnt(2)
	v_mfma_scale_f32_32x32x64_f8f6f4 v[82:97], v[122:129], v[130:137], v[82:97], v194, v193 op_sel_hi:[0,0,0]
	v_exp_f32_e32 v0, v110
	v_exp_f32_e32 v177, v111
	v_exp_f32_e32 v179, v112
	v_exp_f32_e32 v254, v113
	v_add_f32_e32 v219, v0, v219
	v_add_f32_e32 v219, v177, v219
	v_cvt_pk_fp8_f32 v253, v0, v177
	v_add_f32_e32 v219, v179, v219
	v_add_f32_e32 v219, v254, v219
	v_cvt_pk_fp8_f32 v253, v179, v254 op_sel:[0,0,1]
	ds_read_b128 v[122:125], v185 offset:8192
	ds_read_b128 v[126:129], v186 offset:8192
	ds_read_b128 v[114:117], v185 offset:10240
	ds_read_b128 v[118:121], v186 offset:10240
	ds_read_b128 v[106:109], v185 offset:12288
	ds_read_b128 v[110:113], v186 offset:12288
	ds_read_b128 v[98:101], v185 offset:14336
	ds_read_b128 v[102:105], v186 offset:14336
	s_waitcnt lgkmcnt(8)
	v_mfma_scale_f32_32x32x64_f8f6f4 v[66:81], v[222:229], v[130:137], v[66:81], v194, v193 op_sel_hi:[0,0,0]
	v_mov_b32_e32 v0, v219
	s_nop 1
	v_permlane32_swap_b32_e32 v219, v0
	v_add_f32_e32 v219, v219, v0
	v_fma_f32 v209, v209, v221, v219
	v_max_f32_e32 v177, v82, v83
	v_max3_f32 v177, v177, v84, v85
	v_max3_f32 v177, v177, v86, v87
	v_max3_f32 v177, v177, v88, v89
	v_max3_f32 v177, v177, v90, v91
	v_max3_f32 v177, v177, v92, v93
	v_max3_f32 v177, v177, v94, v95
	v_max3_f32 v177, v177, v96, v97
	s_waitcnt lgkmcnt(6)
	v_mfma_scale_f32_32x32x64_f8f6f4 v[50:65], v[246:253], v[122:129], v[50:65], v194, v194 op_sel_hi:[0,0,0]
	v_max_f32_e32 v0, v66, v67
	v_max3_f32 v0, v0, v68, v69
	v_max3_f32 v0, v0, v70, v71
	s_waitcnt vmcnt(0)
	ds_write_b128 v210, v[158:161]
	ds_write_b128 v211, v[162:165] offset:16384
	s_waitcnt lgkmcnt(6)
	v_mfma_scale_f32_32x32x64_f8f6f4 v[34:49], v[246:253], v[114:121], v[34:49], v194, v194 op_sel_hi:[0,0,0]
	s_waitcnt lgkmcnt(0)
	s_barrier
	v_max3_f32 v0, v0, v72, v73
	v_max3_f32 v0, v0, v74, v75
	v_max3_f32 v0, v0, v76, v77
	s_waitcnt lgkmcnt(2)
	v_mfma_scale_f32_32x32x64_f8f6f4 v[18:33], v[246:253], v[106:113], v[18:33], v194, v194 op_sel_hi:[0,0,0]
	v_max3_f32 v0, v0, v78, v79
	v_max3_f32 v0, v0, v80, v81
	v_max_f32_e32 v177, v177, v0
	v_mov_b32_e32 v0, v177
	v_mov_b32_e32 v218, 1.0
	s_waitcnt lgkmcnt(0)
	v_mfma_scale_f32_32x32x64_f8f6f4 v[2:17], v[246:253], v[98:105], v[2:17], v194, v194 op_sel_hi:[0,0,0]
	s_nop 0
	v_permlane32_swap_b32_e32 v177, v0
	v_max_f32_e32 v177, v177, v0
	v_cmp_ge_f32_e32 vcc, s90, v177
	s_cmp_eq_u64 vcc, exec
	s_cbranch_scc0 .Lmla_q1_newmax
